# attention rewritten by hand: head-partitioned by XCD (KV8 head-major), 8 keys per load, 32 rows in flight per wave, softmax in registers
# speedup vs baseline: 1.0809x; 1.0048x over previous
; __device__ __forceinline__ float bf_lo(unsigned v) { return __uint_as_float(v << 16); }
; __global__ void __launch_bounds__(512, 2) mega(Params p) {
;     ...
;             for (int t = gw; t < S_; t += ngw) {
; #pragma unroll
;                 for (int which = 0; which < 2; ++which) {
;                     u32x4* ptr = (u32x4*)(Z + (size_t)t * ZLD + (which ? OFF_K : OFF_Q) + lane * 16);
;                     const u32x4 a = ptr[0], b = ptr[1];
;                     float f[16] = {bf_lo(a.x), bf_hi(a.x), bf_lo(a.y), bf_hi(a.y), bf_lo(a.z), bf_hi(a.z), bf_lo(a.w), bf_hi(a.w), bf_lo(b.x), bf_hi(b.x), bf_lo(b.y), bf_hi(b.y), bf_lo(b.z), bf_hi(b.z), bf_lo(b.w), bf_hi(b.w)};
;                     float ss = 0.f;
; #pragma unroll
;                     for (int e = 0; e < 16; ++e) ss = fmaf(f[e], f[e], ss);
;                     ss += __shfl_xor(ss, 1); ss += __shfl_xor(ss, 2); ss += __shfl_xor(ss, 4);
;                     const float rinv = 1.f / sqrtf(ss * (1.f / 128.f) + EPS_);
; #pragma unroll
;                     for (int e = 0; e < 16; ++e) f[e] = f[e] * rinv * (which ? 1.f : gq[e]);
;                     if (which == 0) {
;                         u32x4 oa, ob; oa.x = cvt_pk_bf16(f[0], f[1]); oa.y = cvt_pk_bf16(f[2], f[3]); oa.z = cvt_pk_bf16(f[4], f[5]); oa.w = cvt_pk_bf16(f[6], f[7]);
;                         ob.x = cvt_pk_bf16(f[8], f[9]); ob.y = cvt_pk_bf16(f[10], f[11]); ob.z = cvt_pk_bf16(f[12], f[13]); ob.w = cvt_pk_bf16(f[14], f[15]);
;                         ptr[0] = oa; ptr[1] = ob;
;                     } else {
;                         int w0 = 0, w1 = 0, w2 = 0, w3 = 0;
;                         w0 = __builtin_amdgcn_cvt_pk_fp8_f32(f[0], f[1], w0, false); w0 = __builtin_amdgcn_cvt_pk_fp8_f32(f[2], f[3], w0, true);
;                         w1 = __builtin_amdgcn_cvt_pk_fp8_f32(f[4], f[5], w1, false); w1 = __builtin_amdgcn_cvt_pk_fp8_f32(f[6], f[7], w1, true);
;                         w2 = __builtin_amdgcn_cvt_pk_fp8_f32(f[8], f[9], w2, false); w2 = __builtin_amdgcn_cvt_pk_fp8_f32(f[10], f[11], w2, true);
;                         w3 = __builtin_amdgcn_cvt_pk_fp8_f32(f[12], f[13], w3, false); w3 = __builtin_amdgcn_cvt_pk_fp8_f32(f[14], f[15], w3, true);
;                         u32x4 o8; o8.x = (unsigned)w0; o8.y = (unsigned)w1; o8.z = (unsigned)w2; o8.w = (unsigned)w3;
;                         *(u32x4*)(KV8 + (size_t)t * 2048 + lane * 16) = o8;
.LBB0_1175:
	v_lshl_add_u64 v[8:9], s[60:61], 0, v[4:5]
	s_mov_b64 s[6:7], 0xa000800
	v_add_co_u32_e32 v48, vcc, 0xa000000, v8
	v_lshl_add_u64 v[36:37], v[8:9], 0, s[6:7]
	s_nop 0
	v_addc_co_u32_e32 v49, vcc, 0, v9, vcc
	global_load_dwordx4 v[32:35], v[48:49], off offset:2048
	s_nop 0
	global_load_dwordx4 v[36:39], v[36:37], off offset:16
	s_mov_b64 s[12:13], 0xa001000
	v_lshl_add_u64 v[164:165], v[8:9], 0, s[12:13]
	global_load_dwordx4 v[148:151], v[164:165], off
	global_load_dwordx4 v[152:155], v[164:165], off offset:16
	global_load_dwordx4 v[156:159], v[164:165], off offset:2048
	global_load_dwordx4 v[160:163], v[164:165], off offset:2064
	s_mov_b32 s4, 0xa001000
	v_add_co_u32_e64 v50, s[6:7], s4, v8
	s_mov_b64 s[8:9], 0xa001000
	s_nop 0
	v_addc_co_u32_e64 v51, s[6:7], 0, v9, s[6:7]
	v_lshl_add_u64 v[44:45], v[8:9], 0, s[8:9]
	v_lshl_add_u64 v[10:11], s[60:61], 0, v[6:7]
	v_and_b32_e32 v166, 0xfffff800, v6
	v_lshrrev_b32_e32 v166, 3, v166
	v_and_b32_e32 v167, 0x7f, v6
	v_add_u32_e32 v166, v166, v167
	v_bfe_u32 v167, v6, 7, 3
	v_lshl_add_u32 v166, v167, 22, v166
	v_mov_b32_e32 v167, 0
	v_lshl_add_u64 v[166:167], s[60:61], 0, v[166:167]
	s_mov_b64 s[14:15], 0x1b800000
	v_lshl_add_u64 v[166:167], v[166:167], 0, s[14:15]
	v_mov_b32_e32 v0, 0
	v_mov_b32_e32 v1, 0
	v_mov_b32_e32 v2, 0
	v_mov_b32_e32 v3, 0
	s_add_i32 s10, s10, s82
	v_lshl_add_u64 v[6:7], v[6:7], 0, s[50:51]
	v_lshl_add_u64 v[4:5], v[4:5], 0, s[52:53]
	s_cmpk_gt_i32 s10, 0x3fff
	s_waitcnt vmcnt(5)
	v_lshlrev_b32_e32 v31, 16, v32
	v_and_b32_e32 v32, 0xffff0000, v32
	v_fma_f32 v53, v31, v31, 0
	v_lshlrev_b32_e32 v40, 16, v33
	v_fmac_f32_e32 v53, v32, v32
	v_and_b32_e32 v33, 0xffff0000, v33
	v_fmac_f32_e32 v53, v40, v40
	v_lshlrev_b32_e32 v41, 16, v34
	v_fmac_f32_e32 v53, v33, v33
	v_and_b32_e32 v34, 0xffff0000, v34
	v_fmac_f32_e32 v53, v41, v41
	v_lshlrev_b32_e32 v42, 16, v35
	v_fmac_f32_e32 v53, v34, v34
	v_and_b32_e32 v35, 0xffff0000, v35
	v_fmac_f32_e32 v53, v42, v42
	s_waitcnt vmcnt(4)
	v_lshlrev_b32_e32 v43, 16, v36
	v_fmac_f32_e32 v53, v35, v35
	v_and_b32_e32 v36, 0xffff0000, v36
	v_fmac_f32_e32 v53, v43, v43
	v_lshlrev_b32_e32 v46, 16, v37
	v_fmac_f32_e32 v53, v36, v36
	v_and_b32_e32 v37, 0xffff0000, v37
	v_fmac_f32_e32 v53, v46, v46
	v_lshlrev_b32_e32 v47, 16, v38
	v_fmac_f32_e32 v53, v37, v37
	v_and_b32_e32 v38, 0xffff0000, v38
	v_fmac_f32_e32 v53, v47, v47
	v_lshlrev_b32_e32 v52, 16, v39
	v_fmac_f32_e32 v53, v38, v38
	v_and_b32_e32 v39, 0xffff0000, v39
	v_fmac_f32_e32 v53, v52, v52
	v_fmac_f32_e32 v53, v39, v39
	ds_bpermute_b32 v54, v12, v53
	s_waitcnt lgkmcnt(0)
	v_add_f32_e32 v53, v53, v54
	ds_bpermute_b32 v54, v13, v53
	s_waitcnt lgkmcnt(0)
	v_add_f32_e32 v53, v53, v54
	ds_bpermute_b32 v54, v14, v53
	s_waitcnt lgkmcnt(0)
	v_add_f32_e32 v53, v53, v54
	v_fmamk_f32 v53, v53, 0x3c000000, v121
	v_mul_f32_e32 v54, 0x4f800000, v53
	v_cmp_gt_f32_e32 vcc, s39, v53
	s_nop 1
	v_cndmask_b32_e32 v53, v53, v54, vcc
	v_sqrt_f32_e32 v54, v53
	s_nop 0
	v_add_u32_e32 v55, -1, v54
	v_add_u32_e32 v56, 1, v54
	v_fma_f32 v57, -v55, v54, v53
	v_fma_f32 v58, -v56, v54, v53
	v_cmp_ge_f32_e64 s[6:7], 0, v57
	s_nop 1
	v_cndmask_b32_e64 v54, v54, v55, s[6:7]
	v_cmp_lt_f32_e64 s[6:7], 0, v58
	s_nop 1
	v_cndmask_b32_e64 v54, v54, v56, s[6:7]
	v_mul_f32_e32 v55, 0x37800000, v54
	v_cndmask_b32_e32 v54, v54, v55, vcc
	v_cmp_class_f32_e32 vcc, v53, v122
	s_mov_b32 s6, 0x1b800000
	s_nop 0
	v_cndmask_b32_e32 v53, v54, v53, vcc
	v_div_scale_f32 v54, s[4:5], v53, v53, 1.0
	v_rcp_f32_e32 v56, v54
	v_div_scale_f32 v55, vcc, 1.0, v53, 1.0
	s_mov_b64 s[4:5], 0xa001800
	v_fma_f32 v57, -v54, v56, 1.0
	v_fmac_f32_e32 v56, v57, v56
	v_mul_f32_e32 v57, v55, v56
	v_fma_f32 v58, -v54, v57, v55
	v_fmac_f32_e32 v57, v58, v56
	v_fma_f32 v54, -v54, v57, v55
	v_div_fmas_f32 v54, v54, v56, v57
	v_div_fixup_f32 v53, v54, v53, 1.0
	v_mul_f32_e32 v39, v53, v39
	v_mul_f32_e32 v38, v53, v38
	v_mul_f32_e32 v47, v53, v47
	v_mul_f32_e32 v37, v53, v37
	v_mul_f32_e32 v46, v53, v46
	v_mul_f32_e32 v36, v53, v36
	v_mul_f32_e32 v43, v53, v43
	v_mul_f32_e32 v35, v53, v35
	v_mul_f32_e32 v42, v53, v42
	v_mul_f32_e32 v34, v53, v34
	v_mul_f32_e32 v41, v53, v41
	v_mul_f32_e32 v33, v53, v33
	v_mul_f32_e32 v40, v53, v40
	v_mul_f32_e32 v32, v53, v32
	v_mul_f32_e32 v52, v53, v52
	v_mul_f32_e32 v31, v53, v31
	v_mul_f32_e32 v39, v39, v30
	v_mul_f32_e32 v38, v38, v28
	v_mul_f32_e32 v47, v47, v27
	v_mul_f32_e32 v37, v37, v26
	v_mul_f32_e32 v46, v46, v25
	v_mul_f32_e32 v36, v36, v24
	v_mul_f32_e32 v43, v43, v23
	v_mul_f32_e32 v35, v35, v22
	v_mul_f32_e32 v42, v42, v21
	v_mul_f32_e32 v34, v34, v20
	v_mul_f32_e32 v41, v41, v19
	v_mul_f32_e32 v33, v33, v18
	v_mul_f32_e32 v40, v40, v17
	v_mul_f32_e32 v32, v32, v16
	v_mul_f32_e32 v52, v52, v29
	v_mul_f32_e32 v31, v31, v15
	v_cvt_pk_bf16_f32 v32, v31, v32
	v_cvt_pk_bf16_f32 v33, v40, v33
	v_cvt_pk_bf16_f32 v34, v41, v34
	v_cvt_pk_bf16_f32 v35, v42, v35
	v_cvt_pk_bf16_f32 v36, v43, v36
	v_cvt_pk_bf16_f32 v37, v46, v37
	v_cvt_pk_bf16_f32 v38, v47, v38
	v_cvt_pk_bf16_f32 v39, v52, v39
	s_waitcnt vmcnt(2)
; __device__ __forceinline__ float bf_lo(unsigned v) { return __uint_as_float(v << 16); }
; __device__ __forceinline__ float bf_hi(unsigned v) { return __uint_as_float(v & 0xffff0000u); }
; __global__ void __launch_bounds__(512, 2) mega(Params p) {
;     ...
;                         int w0 = 0, w1 = 0, w2 = 0, w3 = 0;
;                         w0 = __builtin_amdgcn_cvt_pk_fp8_f32(f[0], f[1], w0, false); w0 = __builtin_amdgcn_cvt_pk_fp8_f32(f[2], f[3], w0, true);
;                         w1 = __builtin_amdgcn_cvt_pk_fp8_f32(f[4], f[5], w1, false); w1 = __builtin_amdgcn_cvt_pk_fp8_f32(f[6], f[7], w1, true);
;                         w2 = __builtin_amdgcn_cvt_pk_fp8_f32(f[8], f[9], w2, false); w2 = __builtin_amdgcn_cvt_pk_fp8_f32(f[10], f[11], w2, true);
;                         w3 = __builtin_amdgcn_cvt_pk_fp8_f32(f[12], f[13], w3, false); w3 = __builtin_amdgcn_cvt_pk_fp8_f32(f[14], f[15], w3, true);
;                         u32x4 o8; o8.x = (unsigned)w0; o8.y = (unsigned)w1; o8.z = (unsigned)w2; o8.w = (unsigned)w3;
;                         *(u32x4*)(KV8 + (size_t)t * 2048 + lane * 16) = o8;
;                     }
;                 }
;                 {
;                     const u32x4* ptr = (const u32x4*)(Z + (size_t)t * ZLD + OFF_V + lane * 16);
;                     const u32x4 a = ptr[0], b = ptr[1];
;                     int w0 = 0, w1 = 0, w2 = 0, w3 = 0;
;                     w0 = __builtin_amdgcn_cvt_pk_fp8_f32(bf_lo(a.x), bf_hi(a.x), w0, false); w0 = __builtin_amdgcn_cvt_pk_fp8_f32(bf_lo(a.y), bf_hi(a.y), w0, true);
;                     w1 = __builtin_amdgcn_cvt_pk_fp8_f32(bf_lo(a.z), bf_hi(a.z), w1, false); w1 = __builtin_amdgcn_cvt_pk_fp8_f32(bf_lo(a.w), bf_hi(a.w), w1, true);
;                     w2 = __builtin_amdgcn_cvt_pk_fp8_f32(bf_lo(b.x), bf_hi(b.x), w2, false); w2 = __builtin_amdgcn_cvt_pk_fp8_f32(bf_lo(b.y), bf_hi(b.y), w2, true);
;                     w3 = __builtin_amdgcn_cvt_pk_fp8_f32(bf_lo(b.z), bf_hi(b.z), w3, false); w3 = __builtin_amdgcn_cvt_pk_fp8_f32(bf_lo(b.w), bf_hi(b.w), w3, true);
;                     u32x4 o8; o8.x = (unsigned)w0; o8.y = (unsigned)w1; o8.z = (unsigned)w2; o8.w = (unsigned)w3;
;                     *(u32x4*)(KV8 + (size_t)t * 2048 + 1024 + lane * 16) = o8;
	v_mov_b32_e32 v40, v148
	v_mov_b32_e32 v41, v149
	v_mov_b32_e32 v42, v150
	v_mov_b32_e32 v43, v151
	s_nop 0
	v_mov_b32_e32 v44, v152
	v_mov_b32_e32 v45, v153
	v_mov_b32_e32 v46, v154
	v_mov_b32_e32 v47, v155
	v_add_co_u32_e32 v52, vcc, s6, v10
	global_store_dwordx4 v[48:49], v[32:35], off offset:2048
	global_store_dwordx4 v[48:49], v[36:39], off offset:2064
	v_addc_co_u32_e32 v53, vcc, 0, v11, vcc
	v_lshl_add_u64 v[8:9], v[8:9], 0, s[4:5]
	v_lshlrev_b32_e32 v10, 16, v40
	v_and_b32_e32 v11, 0xffff0000, v40
	v_lshlrev_b32_e32 v39, 16, v45
	v_and_b32_e32 v40, 0xffff0000, v45
	v_fma_f32 v45, v10, v10, 0
	v_lshlrev_b32_e32 v31, 16, v41
	v_fmac_f32_e32 v45, v11, v11
	v_and_b32_e32 v32, 0xffff0000, v41
	v_fmac_f32_e32 v45, v31, v31
	v_lshlrev_b32_e32 v33, 16, v42
	v_fmac_f32_e32 v45, v32, v32
	v_and_b32_e32 v34, 0xffff0000, v42
	v_fmac_f32_e32 v45, v33, v33
	v_lshlrev_b32_e32 v35, 16, v43
	v_fmac_f32_e32 v45, v34, v34
	v_and_b32_e32 v36, 0xffff0000, v43
	v_fmac_f32_e32 v45, v35, v35
	v_lshlrev_b32_e32 v37, 16, v44
	v_fmac_f32_e32 v45, v36, v36
	v_and_b32_e32 v38, 0xffff0000, v44
	v_fmac_f32_e32 v45, v37, v37
	v_fmac_f32_e32 v45, v38, v38
	v_fmac_f32_e32 v45, v39, v39
	v_lshlrev_b32_e32 v41, 16, v46
	v_fmac_f32_e32 v45, v40, v40
	v_and_b32_e32 v42, 0xffff0000, v46
	v_fmac_f32_e32 v45, v41, v41
	v_lshlrev_b32_e32 v43, 16, v47
	v_fmac_f32_e32 v45, v42, v42
	v_and_b32_e32 v44, 0xffff0000, v47
	v_fmac_f32_e32 v45, v43, v43
	v_fmac_f32_e32 v45, v44, v44
	ds_bpermute_b32 v46, v12, v45
	s_waitcnt lgkmcnt(0)
	v_add_f32_e32 v45, v45, v46
	ds_bpermute_b32 v46, v13, v45
	s_waitcnt lgkmcnt(0)
	v_add_f32_e32 v45, v45, v46
	ds_bpermute_b32 v46, v14, v45
	s_waitcnt lgkmcnt(0)
	v_add_f32_e32 v45, v45, v46
	v_fmamk_f32 v45, v45, 0x3c000000, v121
	v_mul_f32_e32 v46, 0x4f800000, v45
	v_cmp_gt_f32_e32 vcc, s39, v45
	s_nop 1
	v_cndmask_b32_e32 v45, v45, v46, vcc
	v_sqrt_f32_e32 v46, v45
	s_nop 0
	v_add_u32_e32 v47, -1, v46
	v_add_u32_e32 v48, 1, v46
	v_fma_f32 v49, -v47, v46, v45
	v_fma_f32 v54, -v48, v46, v45
	v_cmp_ge_f32_e64 s[6:7], 0, v49
	s_nop 1
	v_cndmask_b32_e64 v46, v46, v47, s[6:7]
	v_cmp_lt_f32_e64 s[6:7], 0, v54
	s_nop 1
	v_cndmask_b32_e64 v46, v46, v48, s[6:7]
	v_mul_f32_e32 v47, 0x37800000, v46
	v_cndmask_b32_e32 v46, v46, v47, vcc
	v_cmp_class_f32_e32 vcc, v45, v122
	s_nop 1
	v_cndmask_b32_e32 v45, v46, v45, vcc
	v_div_scale_f32 v46, s[4:5], v45, v45, 1.0
	v_rcp_f32_e32 v48, v46
	v_div_scale_f32 v47, vcc, 1.0, v45, 1.0
	v_fma_f32 v49, -v46, v48, 1.0
	v_fmac_f32_e32 v48, v49, v48
	v_mul_f32_e32 v49, v47, v48
	v_fma_f32 v54, -v46, v49, v47
	v_fmac_f32_e32 v49, v54, v48
	v_fma_f32 v46, -v46, v49, v47
	v_div_fmas_f32 v46, v46, v48, v49
	v_div_fixup_f32 v45, v46, v45, 1.0
	v_mul_f32_e32 v42, v45, v42
	v_mul_f32_e32 v41, v45, v41
	v_mul_f32_e32 v38, v45, v38
	v_mul_f32_e32 v37, v45, v37
	v_mul_f32_e32 v34, v45, v34
	v_mul_f32_e32 v33, v45, v33
	v_mul_f32_e32 v11, v45, v11
	v_mul_f32_e32 v10, v45, v10
	v_cvt_pk_fp8_f32 v0, v10, v11
	v_cvt_pk_fp8_f32 v1, v33, v34
	v_cvt_pk_fp8_f32 v2, v37, v38
	v_cvt_pk_fp8_f32 v3, v41, v42
	v_mul_f32_e32 v44, v45, v44
	v_mul_f32_e32 v43, v45, v43
	v_mul_f32_e32 v40, v45, v40
	v_mul_f32_e32 v39, v45, v39
	v_mul_f32_e32 v36, v45, v36
	v_mul_f32_e32 v35, v45, v35
	v_mul_f32_e32 v32, v45, v32
	v_mul_f32_e32 v31, v45, v31
	v_cvt_pk_fp8_f32 v0, v31, v32 op_sel:[0,0,1]
	v_cvt_pk_fp8_f32 v1, v35, v36 op_sel:[0,0,1]
	v_cvt_pk_fp8_f32 v2, v39, v40 op_sel:[0,0,1]
	v_cvt_pk_fp8_f32 v3, v43, v44 op_sel:[0,0,1]
	v_mov_b32_e32 v32, 0
	v_mov_b32_e32 v33, 0
	v_mov_b32_e32 v34, 0
	global_store_dwordx4 v[166:167], v[0:3], off
	s_waitcnt vmcnt(3)
	v_mov_b32_e32 v8, v160
	v_mov_b32_e32 v9, v161
	v_mov_b32_e32 v10, v162
	v_mov_b32_e32 v11, v163
	s_nop 0
	v_mov_b32_e32 v0, v156
	v_mov_b32_e32 v1, v157
	v_mov_b32_e32 v2, v158
	v_mov_b32_e32 v3, v159
	v_mov_b32_e32 v35, 0
	v_lshlrev_b32_e32 v31, 16, v0
	v_and_b32_e32 v0, 0xffff0000, v0
	v_lshlrev_b32_e32 v37, 16, v2
	v_and_b32_e32 v2, 0xffff0000, v2
	v_lshlrev_b32_e32 v39, 16, v8
	v_and_b32_e32 v8, 0xffff0000, v8
	v_lshlrev_b32_e32 v41, 16, v10
	v_and_b32_e32 v10, 0xffff0000, v10
	v_cvt_pk_fp8_f32 v32, v31, v0
	v_cvt_pk_fp8_f32 v33, v37, v2
	v_cvt_pk_fp8_f32 v34, v39, v8
	v_cvt_pk_fp8_f32 v35, v41, v10
	v_lshlrev_b32_e32 v36, 16, v1
	v_and_b32_e32 v1, 0xffff0000, v1
	v_lshlrev_b32_e32 v38, 16, v3
	v_and_b32_e32 v3, 0xffff0000, v3
	v_lshlrev_b32_e32 v40, 16, v9
	v_and_b32_e32 v9, 0xffff0000, v9
	v_lshlrev_b32_e32 v42, 16, v11
	v_and_b32_e32 v11, 0xffff0000, v11
	v_cvt_pk_fp8_f32 v32, v36, v1 op_sel:[0,0,1]
	v_cvt_pk_fp8_f32 v33, v38, v3 op_sel:[0,0,1]
	v_cvt_pk_fp8_f32 v34, v40, v9 op_sel:[0,0,1]
	v_cvt_pk_fp8_f32 v35, v42, v11 op_sel:[0,0,1]
	global_store_dwordx4 v[166:167], v[32:35], off offset:128
	s_cbranch_scc0 .LBB0_1175
	s_branch .LBB0_352

; #define LAS __attribute__((address_space(3)))
; __device__ __forceinline__ float bf_lo(unsigned v) { return __uint_as_float(v << 16); }
; __device__ __forceinline__ float bf_hi(unsigned v) { return __uint_as_float(v & 0xffff0000u); }
; __device__ __forceinline__ int lane_id() { int l; asm volatile("v_mbcnt_lo_u32_b32 %0, -1, 0\n\tv_mbcnt_hi_u32_b32 %0, -1, %0\n\ts_nop 1" : "=v"(l)); return l; }
; __device__ __forceinline__ void attn_query8(const unsigned char* __restrict__ KV8, const bf16_t* __restrict__ Z, const int* __restrict__ SEL, bf16_t* __restrict__ YMIX, int t, LAS float* sbuf  ) {
;     const int lane = lane_id(), hd = lane >> 3;
;     const int nsel = (t + 1 < 256) ? (t + 1) : 256, nb = (nsel + 7) >> 3;
;     int iv[4];
; #pragma unroll
;     for (int jj = 0; jj < 4; ++jj) { const int e = lane + 64 * jj; iv[jj] = (e < nsel) ? SEL[(size_t)t * 256 + e] : 0; }
;     f32x2v qf[8];
;     { const u32x4* qp = (const u32x4*)(Z + (size_t)t * ZLD + OFF_Q + lane * 16); const u32x4 a = qp[0], b = qp[1];
;       qf[0] = (f32x2v){bf_lo(a.x), bf_hi(a.x)}; qf[1] = (f32x2v){bf_lo(a.y), bf_hi(a.y)}; qf[2] = (f32x2v){bf_lo(a.z), bf_hi(a.z)}; qf[3] = (f32x2v){bf_lo(a.w), bf_hi(a.w)};
;       qf[4] = (f32x2v){bf_lo(b.x), bf_hi(b.x)}; qf[5] = (f32x2v){bf_lo(b.y), bf_hi(b.y)}; qf[6] = (f32x2v){bf_lo(b.z), bf_hi(b.z)}; qf[7] = (f32x2v){bf_lo(b.w), bf_hi(b.w)}; }
;     const __amdgpu_buffer_rsrc_t rs = __builtin_amdgcn_make_buffer_rsrc((void*)KV8, 0, 0x7fffffff, 0x00020000);
;     const int lvo = lane * 16;
;     LAS float* srow = sbuf + hd * 256;
;     u32x4 A[8], B[8], C[8];
;     const int lb = nb - 1;
;     ...
;     kv8_issue(A, rs, lvo, 0, iv, 0);
;     kv8_issue(B, rs, lvo, 0, iv, CLAMPB(1));
; #pragma unroll 1
;     for (int b = 0; b < nb; b += 3) {
;         kv8_issue(C, rs, lvo, 0, iv, CLAMPB(b + 2));
.LBB0_1247:
	v_readlane_b32 s4, v248, 4
	v_readlane_b32 s5, v248, 5
	s_andn2_b64 vcc, exec, s[4:5]
	s_waitcnt vmcnt(0) lgkmcnt(0)
	s_barrier
	s_cbranch_vccnz .LBB0_1377
	s_mul_i32 s0, s81, 0x800
	s_and_b32 s5, s2, 7
	s_lshr_b32 s8, s2, 3
	s_lshl_b32 s8, s8, 3
	s_add_i32 s80, s8, s81
	s_lshl_b32 s8, s5, 22
	s_add_u32 s16, s60, 0x1b800000
	s_addc_u32 s17, s61, 0
	s_add_u32 s16, s16, s8
	s_addc_u32 s17, s17, 0
	s_and_b32 s17, s17, 0xffff
	s_mov_b32 s18, 0x400000
	s_mov_b32 s19, 0x20000
	s_mov_b32 s26, 0
	s_movk_i32 s27, 0x80
	s_mov_b32 s28, 0x3fb8aa3b
	v_and_b32_e32 v132, 7, v144
	v_lshlrev_b32_e32 v138, 4, v132
	v_lshrrev_b32_e32 v145, 3, v144
	v_lshl_add_u32 v139, v145, 7, s0
	v_lshl_add_u32 v148, v132, 7, s0
	v_lshl_add_u32 v148, v145, 2, v148
	v_xor_b32_e32 v140, 16, v144
	v_lshlrev_b32_e32 v140, 2, v140
	v_xor_b32_e32 v141, 32, v144
	v_lshlrev_b32_e32 v141, 2, v141
	v_mov_b32_e32 v142, 0xff800000
	v_lshlrev_b32_e32 v147, 2, v144
	s_lshl_b32 s8, s5, 8
	v_lshl_add_u32 v146, v132, 5, s8
	s_min_i32 s8, s80, 0xff
	s_add_i32 s8, s8, 1
	s_lshl_b32 s10, s80, 10
	s_add_u32 s10, s1, s10
	s_addc_u32 s11, s73, 0
	v_mov_b32_e32 v240, 0
	v_add_u32_e32 v133, 0, v144
	v_cmp_gt_i32_e32 vcc, s8, v133
	s_and_saveexec_b64 s[12:13], vcc
	global_load_dword v240, v147, s[10:11] offset:0
	s_mov_b64 exec, s[12:13]
	v_mov_b32_e32 v241, 0
	v_add_u32_e32 v133, 64, v144
	v_cmp_gt_i32_e32 vcc, s8, v133
	s_and_saveexec_b64 s[12:13], vcc
	global_load_dword v241, v147, s[10:11] offset:256
	s_mov_b64 exec, s[12:13]
	v_mov_b32_e32 v242, 0
	v_add_u32_e32 v133, 128, v144
	v_cmp_gt_i32_e32 vcc, s8, v133
	s_and_saveexec_b64 s[12:13], vcc
	global_load_dword v242, v147, s[10:11] offset:512
	s_mov_b64 exec, s[12:13]
	v_mov_b32_e32 v243, 0
	v_add_u32_e32 v133, 192, v144
	v_cmp_gt_i32_e32 vcc, s8, v133
	s_and_saveexec_b64 s[12:13], vcc
	global_load_dword v243, v147, s[10:11] offset:768
	s_mov_b64 exec, s[12:13]
	s_mul_i32 s10, s80, 0x2a00
	s_mul_hi_i32 s11, s80, 0x2a00
	s_add_u32 s10, s42, s10
	s_addc_u32 s11, s43, s11
	global_load_dwordx4 v[244:247], v146, s[10:11] offset:2048
.Latt_unit:
	s_min_i32 s4, s80, 0xff
	s_add_i32 s4, s4, 1
	v_sub_u32_e32 v143, s4, v145
	s_mul_i32 s10, s80, 0x2a00
	s_mul_hi_i32 s11, s80, 0x2a00
	s_add_u32 s10, s42, s10
	s_addc_u32 s11, s43, s11
	global_load_dwordx4 v[214:217], v146, s[10:11] offset:2064
	s_waitcnt vmcnt(1)
	ds_write_b32 v148, v240 offset:0
	ds_write_b32 v148, v241 offset:32
	ds_write_b32 v148, v242 offset:64
	ds_write_b32 v148, v243 offset:96
	v_lshlrev_b32_e32 v182, 16, v244
	v_and_b32_e32 v183, 0xffff0000, v244
	v_lshlrev_b32_e32 v184, 16, v245
	v_and_b32_e32 v185, 0xffff0000, v245
	v_lshlrev_b32_e32 v186, 16, v246
	v_and_b32_e32 v187, 0xffff0000, v246
	v_lshlrev_b32_e32 v188, 16, v247
	v_and_b32_e32 v189, 0xffff0000, v247
	s_waitcnt vmcnt(0) lgkmcnt(0)
	v_lshlrev_b32_e32 v190, 16, v214
	v_and_b32_e32 v191, 0xffff0000, v214
	v_lshlrev_b32_e32 v192, 16, v215
	v_and_b32_e32 v193, 0xffff0000, v215
	v_lshlrev_b32_e32 v194, 16, v216
	v_and_b32_e32 v195, 0xffff0000, v216
	v_lshlrev_b32_e32 v196, 16, v217
	v_and_b32_e32 v197, 0xffff0000, v217
	ds_read_b128 v[150:153], v139 offset:0
	ds_read_b128 v[154:157], v139 offset:16
	ds_read_b128 v[158:161], v139 offset:32
	ds_read_b128 v[162:165], v139 offset:48
	ds_read_b128 v[166:169], v139 offset:64
	ds_read_b128 v[170:173], v139 offset:80
	ds_read_b128 v[174:177], v139 offset:96
	ds_read_b128 v[178:181], v139 offset:112
	s_waitcnt lgkmcnt(0)
	v_lshl_add_u32 v150, v150, 8, v138
	v_lshl_add_u32 v151, v151, 8, v138
	v_lshl_add_u32 v152, v152, 8, v138
	v_lshl_add_u32 v153, v153, 8, v138
	v_lshl_add_u32 v154, v154, 8, v138
	v_lshl_add_u32 v155, v155, 8, v138
	v_lshl_add_u32 v156, v156, 8, v138
	v_lshl_add_u32 v157, v157, 8, v138
	v_lshl_add_u32 v158, v158, 8, v138
	v_lshl_add_u32 v159, v159, 8, v138
	v_lshl_add_u32 v160, v160, 8, v138
	v_lshl_add_u32 v161, v161, 8, v138
	v_lshl_add_u32 v162, v162, 8, v138
	v_lshl_add_u32 v163, v163, 8, v138
	v_lshl_add_u32 v164, v164, 8, v138
	v_lshl_add_u32 v165, v165, 8, v138
	v_lshl_add_u32 v166, v166, 8, v138
	v_lshl_add_u32 v167, v167, 8, v138
	v_lshl_add_u32 v168, v168, 8, v138
	v_lshl_add_u32 v169, v169, 8, v138
	v_lshl_add_u32 v170, v170, 8, v138
	v_lshl_add_u32 v171, v171, 8, v138
	v_lshl_add_u32 v172, v172, 8, v138
	v_lshl_add_u32 v173, v173, 8, v138
	v_lshl_add_u32 v174, v174, 8, v138
	v_lshl_add_u32 v175, v175, 8, v138
	v_lshl_add_u32 v176, v176, 8, v138
	v_lshl_add_u32 v177, v177, 8, v138
	v_lshl_add_u32 v178, v178, 8, v138
	v_lshl_add_u32 v179, v179, 8, v138
	v_lshl_add_u32 v180, v180, 8, v138
	v_lshl_add_u32 v181, v181, 8, v138
	buffer_load_dwordx4 v[0:3], v150, s[16:19], s26 offen sc0
	buffer_load_dwordx4 v[4:7], v151, s[16:19], s26 offen sc0
	buffer_load_dwordx4 v[8:11], v152, s[16:19], s26 offen sc0
	buffer_load_dwordx4 v[12:15], v153, s[16:19], s26 offen sc0
	buffer_load_dwordx4 v[16:19], v154, s[16:19], s26 offen sc0
	buffer_load_dwordx4 v[20:23], v155, s[16:19], s26 offen sc0
	buffer_load_dwordx4 v[24:27], v156, s[16:19], s26 offen sc0
	buffer_load_dwordx4 v[28:31], v157, s[16:19], s26 offen sc0
	buffer_load_dwordx4 v[32:35], v158, s[16:19], s26 offen sc0
	buffer_load_dwordx4 v[36:39], v159, s[16:19], s26 offen sc0
	buffer_load_dwordx4 v[40:43], v160, s[16:19], s26 offen sc0
	buffer_load_dwordx4 v[44:47], v161, s[16:19], s26 offen sc0
	buffer_load_dwordx4 v[48:51], v162, s[16:19], s26 offen sc0
	buffer_load_dwordx4 v[52:55], v163, s[16:19], s26 offen sc0
	buffer_load_dwordx4 v[56:59], v164, s[16:19], s26 offen sc0
	buffer_load_dwordx4 v[60:63], v165, s[16:19], s26 offen sc0
	buffer_load_dwordx4 v[64:67], v166, s[16:19], s26 offen sc0
	buffer_load_dwordx4 v[68:71], v167, s[16:19], s26 offen sc0
	buffer_load_dwordx4 v[72:75], v168, s[16:19], s26 offen sc0
	buffer_load_dwordx4 v[76:79], v169, s[16:19], s26 offen sc0
	buffer_load_dwordx4 v[80:83], v170, s[16:19], s26 offen sc0
	buffer_load_dwordx4 v[84:87], v171, s[16:19], s26 offen sc0
	buffer_load_dwordx4 v[88:91], v172, s[16:19], s26 offen sc0
	buffer_load_dwordx4 v[92:95], v173, s[16:19], s26 offen sc0
	buffer_load_dwordx4 v[96:99], v174, s[16:19], s26 offen sc0
	buffer_load_dwordx4 v[100:103], v175, s[16:19], s26 offen sc0
	buffer_load_dwordx4 v[104:107], v176, s[16:19], s26 offen sc0
	buffer_load_dwordx4 v[108:111], v177, s[16:19], s26 offen sc0
	buffer_load_dwordx4 v[112:115], v178, s[16:19], s26 offen sc0
	buffer_load_dwordx4 v[116:119], v179, s[16:19], s26 offen sc0
	buffer_load_dwordx4 v[120:123], v180, s[16:19], s26 offen sc0
	buffer_load_dwordx4 v[124:127], v181, s[16:19], s26 offen sc0
	s_waitcnt vmcnt(31)
; #define LAS __attribute__((address_space(3)))
; __device__ __forceinline__ float red8(float v) { v += dpp_f<0xB1>(v); v += dpp_f<0x4E>(v); v += dpp_f<0x141>(v); return v; }
; __device__ __forceinline__ void kv8_qk(const u32x4 (&buf)[8], const f32x2v (&q2)[8], LAS float* srow, int b, int lane) {
; #pragma unroll
;     for (int u = 0; u < 8; ++u) {
;         const u32x4 k = buf[u];
;         f32x2v s0 = q2[0] * __builtin_amdgcn_cvt_pk_f32_fp8(k.x, false), s1 = q2[1] * __builtin_amdgcn_cvt_pk_f32_fp8(k.x, true);
;         s0 = __builtin_elementwise_fma(q2[2], __builtin_amdgcn_cvt_pk_f32_fp8(k.y, false), s0); s1 = __builtin_elementwise_fma(q2[3], __builtin_amdgcn_cvt_pk_f32_fp8(k.y, true), s1);
;         s0 = __builtin_elementwise_fma(q2[4], __builtin_amdgcn_cvt_pk_f32_fp8(k.z, false), s0); s1 = __builtin_elementwise_fma(q2[5], __builtin_amdgcn_cvt_pk_f32_fp8(k.z, true), s1);
;         s0 = __builtin_elementwise_fma(q2[6], __builtin_amdgcn_cvt_pk_f32_fp8(k.w, false), s0); s1 = __builtin_elementwise_fma(q2[7], __builtin_amdgcn_cvt_pk_f32_fp8(k.w, true), s1);
;         const f32x2v t = s0 + s1;
;         const float s = red8(t.x + t.y);
;         if ((lane & 7) == 0) srow[b * 8 + u] = s;
;     }
	v_cvt_pk_f32_fp8_e32 v[214:215], v0
	v_cvt_pk_f32_fp8_sdwa v[216:217], v0 src0_sel:WORD_1
	v_cvt_pk_f32_fp8_e32 v[218:219], v1
	s_nop 0
	v_cvt_pk_f32_fp8_sdwa v[220:221], v1 src0_sel:WORD_1
	v_cvt_pk_f32_fp8_e32 v[222:223], v2
	v_cvt_pk_f32_fp8_sdwa v[224:225], v2 src0_sel:WORD_1
	v_cvt_pk_f32_fp8_e32 v[226:227], v3
	s_nop 0
	v_cvt_pk_f32_fp8_sdwa v[228:229], v3 src0_sel:WORD_1
	v_pk_mul_f32 v[128:129], v[214:215], v[182:183]
	v_pk_mul_f32 v[130:131], v[216:217], v[184:185]
	v_pk_fma_f32 v[128:129], v[186:187], v[218:219], v[128:129]
	v_pk_fma_f32 v[130:131], v[188:189], v[220:221], v[130:131]
	v_pk_fma_f32 v[128:129], v[190:191], v[222:223], v[128:129]
	v_pk_fma_f32 v[130:131], v[192:193], v[224:225], v[130:131]
	v_pk_fma_f32 v[128:129], v[194:195], v[226:227], v[128:129]
	v_pk_fma_f32 v[130:131], v[196:197], v[228:229], v[130:131]
	buffer_load_dwordx4 v[0:3], v150, s[16:19], s27 offen sc0
	v_pk_add_f32 v[128:129], v[128:129], v[130:131]
	s_nop 0
	v_add_f32_e32 v132, v128, v129
	s_waitcnt vmcnt(31)
	v_cvt_pk_f32_fp8_e32 v[214:215], v4
	v_cvt_pk_f32_fp8_sdwa v[216:217], v4 src0_sel:WORD_1
	v_cvt_pk_f32_fp8_e32 v[218:219], v5
	v_add_f32_dpp v132, v132, v132 quad_perm:[1,0,3,2] row_mask:0xf bank_mask:0xf
	v_cvt_pk_f32_fp8_sdwa v[220:221], v5 src0_sel:WORD_1
	v_cvt_pk_f32_fp8_e32 v[222:223], v6
	v_cvt_pk_f32_fp8_sdwa v[224:225], v6 src0_sel:WORD_1
	v_cvt_pk_f32_fp8_e32 v[226:227], v7
	v_add_f32_dpp v132, v132, v132 quad_perm:[2,3,0,1] row_mask:0xf bank_mask:0xf
	v_cvt_pk_f32_fp8_sdwa v[228:229], v7 src0_sel:WORD_1
	v_pk_mul_f32 v[128:129], v[214:215], v[182:183]
	v_pk_mul_f32 v[130:131], v[216:217], v[184:185]
	v_pk_fma_f32 v[128:129], v[186:187], v[218:219], v[128:129]
	v_pk_fma_f32 v[130:131], v[188:189], v[220:221], v[130:131]
	v_pk_fma_f32 v[128:129], v[190:191], v[222:223], v[128:129]
	v_pk_fma_f32 v[130:131], v[192:193], v[224:225], v[130:131]
	v_pk_fma_f32 v[128:129], v[194:195], v[226:227], v[128:129]
	v_pk_fma_f32 v[130:131], v[196:197], v[228:229], v[130:131]
	buffer_load_dwordx4 v[4:7], v151, s[16:19], s27 offen sc0
	v_pk_add_f32 v[128:129], v[128:129], v[130:131]
	v_add_f32_dpp v150, v132, v132 row_half_mirror row_mask:0xf bank_mask:0xf
	v_add_f32_e32 v133, v128, v129
	s_waitcnt vmcnt(31)
	v_cvt_pk_f32_fp8_e32 v[214:215], v8
	v_cvt_pk_f32_fp8_sdwa v[216:217], v8 src0_sel:WORD_1
	v_cvt_pk_f32_fp8_e32 v[218:219], v9
	v_add_f32_dpp v133, v133, v133 quad_perm:[1,0,3,2] row_mask:0xf bank_mask:0xf
	v_cvt_pk_f32_fp8_sdwa v[220:221], v9 src0_sel:WORD_1
	v_cvt_pk_f32_fp8_e32 v[222:223], v10
	v_cvt_pk_f32_fp8_sdwa v[224:225], v10 src0_sel:WORD_1
	v_cvt_pk_f32_fp8_e32 v[226:227], v11
	v_add_f32_dpp v133, v133, v133 quad_perm:[2,3,0,1] row_mask:0xf bank_mask:0xf
	v_cvt_pk_f32_fp8_sdwa v[228:229], v11 src0_sel:WORD_1
	v_pk_mul_f32 v[128:129], v[214:215], v[182:183]
	v_pk_mul_f32 v[130:131], v[216:217], v[184:185]
	v_pk_fma_f32 v[128:129], v[186:187], v[218:219], v[128:129]
	v_pk_fma_f32 v[130:131], v[188:189], v[220:221], v[130:131]
	v_pk_fma_f32 v[128:129], v[190:191], v[222:223], v[128:129]
	v_pk_fma_f32 v[130:131], v[192:193], v[224:225], v[130:131]
	v_pk_fma_f32 v[128:129], v[194:195], v[226:227], v[128:129]
	v_pk_fma_f32 v[130:131], v[196:197], v[228:229], v[130:131]
	buffer_load_dwordx4 v[8:11], v152, s[16:19], s27 offen sc0
	v_pk_add_f32 v[128:129], v[128:129], v[130:131]
	v_add_f32_dpp v151, v133, v133 row_half_mirror row_mask:0xf bank_mask:0xf
	v_add_f32_e32 v132, v128, v129
	s_waitcnt vmcnt(31)
	v_cvt_pk_f32_fp8_e32 v[214:215], v12
	v_cvt_pk_f32_fp8_sdwa v[216:217], v12 src0_sel:WORD_1
	v_cvt_pk_f32_fp8_e32 v[218:219], v13
	v_add_f32_dpp v132, v132, v132 quad_perm:[1,0,3,2] row_mask:0xf bank_mask:0xf
	v_cvt_pk_f32_fp8_sdwa v[220:221], v13 src0_sel:WORD_1
	v_cvt_pk_f32_fp8_e32 v[222:223], v14
	v_cvt_pk_f32_fp8_sdwa v[224:225], v14 src0_sel:WORD_1
	v_cvt_pk_f32_fp8_e32 v[226:227], v15
	v_add_f32_dpp v132, v132, v132 quad_perm:[2,3,0,1] row_mask:0xf bank_mask:0xf
	v_cvt_pk_f32_fp8_sdwa v[228:229], v15 src0_sel:WORD_1
	v_pk_mul_f32 v[128:129], v[214:215], v[182:183]
	v_pk_mul_f32 v[130:131], v[216:217], v[184:185]
	v_pk_fma_f32 v[128:129], v[186:187], v[218:219], v[128:129]
	v_pk_fma_f32 v[130:131], v[188:189], v[220:221], v[130:131]
	v_pk_fma_f32 v[128:129], v[190:191], v[222:223], v[128:129]
	v_pk_fma_f32 v[130:131], v[192:193], v[224:225], v[130:131]
	v_pk_fma_f32 v[128:129], v[194:195], v[226:227], v[128:129]
	v_pk_fma_f32 v[130:131], v[196:197], v[228:229], v[130:131]
	buffer_load_dwordx4 v[12:15], v153, s[16:19], s27 offen sc0
	v_pk_add_f32 v[128:129], v[128:129], v[130:131]
	v_add_f32_dpp v152, v132, v132 row_half_mirror row_mask:0xf bank_mask:0xf
	v_add_f32_e32 v133, v128, v129
	s_waitcnt vmcnt(31)
	v_cvt_pk_f32_fp8_e32 v[214:215], v16
	v_cvt_pk_f32_fp8_sdwa v[216:217], v16 src0_sel:WORD_1
	v_cvt_pk_f32_fp8_e32 v[218:219], v17
	v_add_f32_dpp v133, v133, v133 quad_perm:[1,0,3,2] row_mask:0xf bank_mask:0xf
	v_cvt_pk_f32_fp8_sdwa v[220:221], v17 src0_sel:WORD_1
	v_cvt_pk_f32_fp8_e32 v[222:223], v18
	v_cvt_pk_f32_fp8_sdwa v[224:225], v18 src0_sel:WORD_1
	v_cvt_pk_f32_fp8_e32 v[226:227], v19
	v_add_f32_dpp v133, v133, v133 quad_perm:[2,3,0,1] row_mask:0xf bank_mask:0xf
	v_cvt_pk_f32_fp8_sdwa v[228:229], v19 src0_sel:WORD_1
	v_pk_mul_f32 v[128:129], v[214:215], v[182:183]
	v_pk_mul_f32 v[130:131], v[216:217], v[184:185]
	v_pk_fma_f32 v[128:129], v[186:187], v[218:219], v[128:129]
	v_pk_fma_f32 v[130:131], v[188:189], v[220:221], v[130:131]
	v_pk_fma_f32 v[128:129], v[190:191], v[222:223], v[128:129]
	v_pk_fma_f32 v[130:131], v[192:193], v[224:225], v[130:131]
	v_pk_fma_f32 v[128:129], v[194:195], v[226:227], v[128:129]
	v_pk_fma_f32 v[130:131], v[196:197], v[228:229], v[130:131]
	buffer_load_dwordx4 v[16:19], v154, s[16:19], s27 offen sc0
	v_pk_add_f32 v[128:129], v[128:129], v[130:131]
	v_add_f32_dpp v153, v133, v133 row_half_mirror row_mask:0xf bank_mask:0xf
	v_add_f32_e32 v132, v128, v129
	s_waitcnt vmcnt(31)
; #define LAS __attribute__((address_space(3)))
; __device__ __forceinline__ float red8(float v) { v += dpp_f<0xB1>(v); v += dpp_f<0x4E>(v); v += dpp_f<0x141>(v); return v; }
; __device__ __forceinline__ void kv8_qk(const u32x4 (&buf)[8], const f32x2v (&q2)[8], LAS float* srow, int b, int lane) {
; #pragma unroll
;     for (int u = 0; u < 8; ++u) {
;         const u32x4 k = buf[u];
;         f32x2v s0 = q2[0] * __builtin_amdgcn_cvt_pk_f32_fp8(k.x, false), s1 = q2[1] * __builtin_amdgcn_cvt_pk_f32_fp8(k.x, true);
;         s0 = __builtin_elementwise_fma(q2[2], __builtin_amdgcn_cvt_pk_f32_fp8(k.y, false), s0); s1 = __builtin_elementwise_fma(q2[3], __builtin_amdgcn_cvt_pk_f32_fp8(k.y, true), s1);
;         s0 = __builtin_elementwise_fma(q2[4], __builtin_amdgcn_cvt_pk_f32_fp8(k.z, false), s0); s1 = __builtin_elementwise_fma(q2[5], __builtin_amdgcn_cvt_pk_f32_fp8(k.z, true), s1);
;         s0 = __builtin_elementwise_fma(q2[6], __builtin_amdgcn_cvt_pk_f32_fp8(k.w, false), s0); s1 = __builtin_elementwise_fma(q2[7], __builtin_amdgcn_cvt_pk_f32_fp8(k.w, true), s1);
;         const f32x2v t = s0 + s1;
;         const float s = red8(t.x + t.y);
;         if ((lane & 7) == 0) srow[b * 8 + u] = s;
;     }
	v_cvt_pk_f32_fp8_e32 v[214:215], v20
	v_cvt_pk_f32_fp8_sdwa v[216:217], v20 src0_sel:WORD_1
	v_cvt_pk_f32_fp8_e32 v[218:219], v21
	v_add_f32_dpp v132, v132, v132 quad_perm:[1,0,3,2] row_mask:0xf bank_mask:0xf
	v_cvt_pk_f32_fp8_sdwa v[220:221], v21 src0_sel:WORD_1
	v_cvt_pk_f32_fp8_e32 v[222:223], v22
	v_cvt_pk_f32_fp8_sdwa v[224:225], v22 src0_sel:WORD_1
	v_cvt_pk_f32_fp8_e32 v[226:227], v23
	v_add_f32_dpp v132, v132, v132 quad_perm:[2,3,0,1] row_mask:0xf bank_mask:0xf
	v_cvt_pk_f32_fp8_sdwa v[228:229], v23 src0_sel:WORD_1
	v_pk_mul_f32 v[128:129], v[214:215], v[182:183]
	v_pk_mul_f32 v[130:131], v[216:217], v[184:185]
	v_pk_fma_f32 v[128:129], v[186:187], v[218:219], v[128:129]
	v_pk_fma_f32 v[130:131], v[188:189], v[220:221], v[130:131]
	v_pk_fma_f32 v[128:129], v[190:191], v[222:223], v[128:129]
	v_pk_fma_f32 v[130:131], v[192:193], v[224:225], v[130:131]
	v_pk_fma_f32 v[128:129], v[194:195], v[226:227], v[128:129]
	v_pk_fma_f32 v[130:131], v[196:197], v[228:229], v[130:131]
	buffer_load_dwordx4 v[20:23], v155, s[16:19], s27 offen sc0
	v_pk_add_f32 v[128:129], v[128:129], v[130:131]
	v_add_f32_dpp v154, v132, v132 row_half_mirror row_mask:0xf bank_mask:0xf
	v_add_f32_e32 v133, v128, v129
	s_waitcnt vmcnt(31)
	v_cvt_pk_f32_fp8_e32 v[214:215], v24
	v_cvt_pk_f32_fp8_sdwa v[216:217], v24 src0_sel:WORD_1
	v_cvt_pk_f32_fp8_e32 v[218:219], v25
	v_add_f32_dpp v133, v133, v133 quad_perm:[1,0,3,2] row_mask:0xf bank_mask:0xf
	v_cvt_pk_f32_fp8_sdwa v[220:221], v25 src0_sel:WORD_1
	v_cvt_pk_f32_fp8_e32 v[222:223], v26
	v_cvt_pk_f32_fp8_sdwa v[224:225], v26 src0_sel:WORD_1
	v_cvt_pk_f32_fp8_e32 v[226:227], v27
	v_add_f32_dpp v133, v133, v133 quad_perm:[2,3,0,1] row_mask:0xf bank_mask:0xf
	v_cvt_pk_f32_fp8_sdwa v[228:229], v27 src0_sel:WORD_1
	v_pk_mul_f32 v[128:129], v[214:215], v[182:183]
	v_pk_mul_f32 v[130:131], v[216:217], v[184:185]
	v_pk_fma_f32 v[128:129], v[186:187], v[218:219], v[128:129]
	v_pk_fma_f32 v[130:131], v[188:189], v[220:221], v[130:131]
	v_pk_fma_f32 v[128:129], v[190:191], v[222:223], v[128:129]
	v_pk_fma_f32 v[130:131], v[192:193], v[224:225], v[130:131]
	v_pk_fma_f32 v[128:129], v[194:195], v[226:227], v[128:129]
	v_pk_fma_f32 v[130:131], v[196:197], v[228:229], v[130:131]
	buffer_load_dwordx4 v[24:27], v156, s[16:19], s27 offen sc0
	v_pk_add_f32 v[128:129], v[128:129], v[130:131]
	v_add_f32_dpp v155, v133, v133 row_half_mirror row_mask:0xf bank_mask:0xf
	v_add_f32_e32 v132, v128, v129
	s_waitcnt vmcnt(31)
	v_cvt_pk_f32_fp8_e32 v[214:215], v28
	v_cvt_pk_f32_fp8_sdwa v[216:217], v28 src0_sel:WORD_1
	v_cvt_pk_f32_fp8_e32 v[218:219], v29
	v_add_f32_dpp v132, v132, v132 quad_perm:[1,0,3,2] row_mask:0xf bank_mask:0xf
	v_cvt_pk_f32_fp8_sdwa v[220:221], v29 src0_sel:WORD_1
	v_cvt_pk_f32_fp8_e32 v[222:223], v30
	v_cvt_pk_f32_fp8_sdwa v[224:225], v30 src0_sel:WORD_1
	v_cvt_pk_f32_fp8_e32 v[226:227], v31
	v_add_f32_dpp v132, v132, v132 quad_perm:[2,3,0,1] row_mask:0xf bank_mask:0xf
	v_cvt_pk_f32_fp8_sdwa v[228:229], v31 src0_sel:WORD_1
	v_pk_mul_f32 v[128:129], v[214:215], v[182:183]
	v_pk_mul_f32 v[130:131], v[216:217], v[184:185]
	v_pk_fma_f32 v[128:129], v[186:187], v[218:219], v[128:129]
	v_pk_fma_f32 v[130:131], v[188:189], v[220:221], v[130:131]
	v_pk_fma_f32 v[128:129], v[190:191], v[222:223], v[128:129]
	v_pk_fma_f32 v[130:131], v[192:193], v[224:225], v[130:131]
	v_pk_fma_f32 v[128:129], v[194:195], v[226:227], v[128:129]
	v_pk_fma_f32 v[130:131], v[196:197], v[228:229], v[130:131]
	buffer_load_dwordx4 v[28:31], v157, s[16:19], s27 offen sc0
	v_pk_add_f32 v[128:129], v[128:129], v[130:131]
	v_add_f32_dpp v156, v132, v132 row_half_mirror row_mask:0xf bank_mask:0xf
	v_add_f32_e32 v133, v128, v129
	s_waitcnt vmcnt(31)
	v_cvt_pk_f32_fp8_e32 v[214:215], v32
	v_cvt_pk_f32_fp8_sdwa v[216:217], v32 src0_sel:WORD_1
	v_cvt_pk_f32_fp8_e32 v[218:219], v33
	v_add_f32_dpp v133, v133, v133 quad_perm:[1,0,3,2] row_mask:0xf bank_mask:0xf
	v_cvt_pk_f32_fp8_sdwa v[220:221], v33 src0_sel:WORD_1
	v_cvt_pk_f32_fp8_e32 v[222:223], v34
	v_cvt_pk_f32_fp8_sdwa v[224:225], v34 src0_sel:WORD_1
	v_cvt_pk_f32_fp8_e32 v[226:227], v35
	v_add_f32_dpp v133, v133, v133 quad_perm:[2,3,0,1] row_mask:0xf bank_mask:0xf
	v_cvt_pk_f32_fp8_sdwa v[228:229], v35 src0_sel:WORD_1
	v_pk_mul_f32 v[128:129], v[214:215], v[182:183]
	v_pk_mul_f32 v[130:131], v[216:217], v[184:185]
	v_pk_fma_f32 v[128:129], v[186:187], v[218:219], v[128:129]
	v_pk_fma_f32 v[130:131], v[188:189], v[220:221], v[130:131]
	v_pk_fma_f32 v[128:129], v[190:191], v[222:223], v[128:129]
	v_pk_fma_f32 v[130:131], v[192:193], v[224:225], v[130:131]
	v_pk_fma_f32 v[128:129], v[194:195], v[226:227], v[128:129]
	v_pk_fma_f32 v[130:131], v[196:197], v[228:229], v[130:131]
	buffer_load_dwordx4 v[32:35], v158, s[16:19], s27 offen sc0
	v_pk_add_f32 v[128:129], v[128:129], v[130:131]
	v_add_f32_dpp v157, v133, v133 row_half_mirror row_mask:0xf bank_mask:0xf
	v_add_f32_e32 v132, v128, v129
	s_waitcnt vmcnt(31)
	v_cvt_pk_f32_fp8_e32 v[214:215], v36
	v_cvt_pk_f32_fp8_sdwa v[216:217], v36 src0_sel:WORD_1
	v_cvt_pk_f32_fp8_e32 v[218:219], v37
	v_add_f32_dpp v132, v132, v132 quad_perm:[1,0,3,2] row_mask:0xf bank_mask:0xf
	v_cvt_pk_f32_fp8_sdwa v[220:221], v37 src0_sel:WORD_1
	v_cvt_pk_f32_fp8_e32 v[222:223], v38
	v_cvt_pk_f32_fp8_sdwa v[224:225], v38 src0_sel:WORD_1
	v_cvt_pk_f32_fp8_e32 v[226:227], v39
	v_add_f32_dpp v132, v132, v132 quad_perm:[2,3,0,1] row_mask:0xf bank_mask:0xf
	v_cvt_pk_f32_fp8_sdwa v[228:229], v39 src0_sel:WORD_1
	v_pk_mul_f32 v[128:129], v[214:215], v[182:183]
	v_pk_mul_f32 v[130:131], v[216:217], v[184:185]
	v_pk_fma_f32 v[128:129], v[186:187], v[218:219], v[128:129]
	v_pk_fma_f32 v[130:131], v[188:189], v[220:221], v[130:131]
	v_pk_fma_f32 v[128:129], v[190:191], v[222:223], v[128:129]
	v_pk_fma_f32 v[130:131], v[192:193], v[224:225], v[130:131]
	v_pk_fma_f32 v[128:129], v[194:195], v[226:227], v[128:129]
	v_pk_fma_f32 v[130:131], v[196:197], v[228:229], v[130:131]
	buffer_load_dwordx4 v[36:39], v159, s[16:19], s27 offen sc0
	v_pk_add_f32 v[128:129], v[128:129], v[130:131]
	v_add_f32_dpp v158, v132, v132 row_half_mirror row_mask:0xf bank_mask:0xf
	v_add_f32_e32 v133, v128, v129
	s_waitcnt vmcnt(31)
; #define LAS __attribute__((address_space(3)))
; __device__ __forceinline__ float red8(float v) { v += dpp_f<0xB1>(v); v += dpp_f<0x4E>(v); v += dpp_f<0x141>(v); return v; }
; __device__ __forceinline__ void kv8_qk(const u32x4 (&buf)[8], const f32x2v (&q2)[8], LAS float* srow, int b, int lane) {
; #pragma unroll
;     for (int u = 0; u < 8; ++u) {
;         const u32x4 k = buf[u];
;         f32x2v s0 = q2[0] * __builtin_amdgcn_cvt_pk_f32_fp8(k.x, false), s1 = q2[1] * __builtin_amdgcn_cvt_pk_f32_fp8(k.x, true);
;         s0 = __builtin_elementwise_fma(q2[2], __builtin_amdgcn_cvt_pk_f32_fp8(k.y, false), s0); s1 = __builtin_elementwise_fma(q2[3], __builtin_amdgcn_cvt_pk_f32_fp8(k.y, true), s1);
;         s0 = __builtin_elementwise_fma(q2[4], __builtin_amdgcn_cvt_pk_f32_fp8(k.z, false), s0); s1 = __builtin_elementwise_fma(q2[5], __builtin_amdgcn_cvt_pk_f32_fp8(k.z, true), s1);
;         s0 = __builtin_elementwise_fma(q2[6], __builtin_amdgcn_cvt_pk_f32_fp8(k.w, false), s0); s1 = __builtin_elementwise_fma(q2[7], __builtin_amdgcn_cvt_pk_f32_fp8(k.w, true), s1);
;         const f32x2v t = s0 + s1;
;         const float s = red8(t.x + t.y);
;         if ((lane & 7) == 0) srow[b * 8 + u] = s;
;     }
	v_cvt_pk_f32_fp8_e32 v[214:215], v40
	v_cvt_pk_f32_fp8_sdwa v[216:217], v40 src0_sel:WORD_1
	v_cvt_pk_f32_fp8_e32 v[218:219], v41
	v_add_f32_dpp v133, v133, v133 quad_perm:[1,0,3,2] row_mask:0xf bank_mask:0xf
	v_cvt_pk_f32_fp8_sdwa v[220:221], v41 src0_sel:WORD_1
	v_cvt_pk_f32_fp8_e32 v[222:223], v42
	v_cvt_pk_f32_fp8_sdwa v[224:225], v42 src0_sel:WORD_1
	v_cvt_pk_f32_fp8_e32 v[226:227], v43
	v_add_f32_dpp v133, v133, v133 quad_perm:[2,3,0,1] row_mask:0xf bank_mask:0xf
	v_cvt_pk_f32_fp8_sdwa v[228:229], v43 src0_sel:WORD_1
	v_pk_mul_f32 v[128:129], v[214:215], v[182:183]
	v_pk_mul_f32 v[130:131], v[216:217], v[184:185]
	v_pk_fma_f32 v[128:129], v[186:187], v[218:219], v[128:129]
	v_pk_fma_f32 v[130:131], v[188:189], v[220:221], v[130:131]
	v_pk_fma_f32 v[128:129], v[190:191], v[222:223], v[128:129]
	v_pk_fma_f32 v[130:131], v[192:193], v[224:225], v[130:131]
	v_pk_fma_f32 v[128:129], v[194:195], v[226:227], v[128:129]
	v_pk_fma_f32 v[130:131], v[196:197], v[228:229], v[130:131]
	buffer_load_dwordx4 v[40:43], v160, s[16:19], s27 offen sc0
	v_pk_add_f32 v[128:129], v[128:129], v[130:131]
	v_add_f32_dpp v159, v133, v133 row_half_mirror row_mask:0xf bank_mask:0xf
	v_add_f32_e32 v132, v128, v129
	s_waitcnt vmcnt(31)
	v_cvt_pk_f32_fp8_e32 v[214:215], v44
	v_cvt_pk_f32_fp8_sdwa v[216:217], v44 src0_sel:WORD_1
	v_cvt_pk_f32_fp8_e32 v[218:219], v45
	v_add_f32_dpp v132, v132, v132 quad_perm:[1,0,3,2] row_mask:0xf bank_mask:0xf
	v_cvt_pk_f32_fp8_sdwa v[220:221], v45 src0_sel:WORD_1
	v_cvt_pk_f32_fp8_e32 v[222:223], v46
	v_cvt_pk_f32_fp8_sdwa v[224:225], v46 src0_sel:WORD_1
	v_cvt_pk_f32_fp8_e32 v[226:227], v47
	v_add_f32_dpp v132, v132, v132 quad_perm:[2,3,0,1] row_mask:0xf bank_mask:0xf
	v_cvt_pk_f32_fp8_sdwa v[228:229], v47 src0_sel:WORD_1
	v_pk_mul_f32 v[128:129], v[214:215], v[182:183]
	v_pk_mul_f32 v[130:131], v[216:217], v[184:185]
	v_pk_fma_f32 v[128:129], v[186:187], v[218:219], v[128:129]
	v_pk_fma_f32 v[130:131], v[188:189], v[220:221], v[130:131]
	v_pk_fma_f32 v[128:129], v[190:191], v[222:223], v[128:129]
	v_pk_fma_f32 v[130:131], v[192:193], v[224:225], v[130:131]
	v_pk_fma_f32 v[128:129], v[194:195], v[226:227], v[128:129]
	v_pk_fma_f32 v[130:131], v[196:197], v[228:229], v[130:131]
	buffer_load_dwordx4 v[44:47], v161, s[16:19], s27 offen sc0
	v_pk_add_f32 v[128:129], v[128:129], v[130:131]
	v_add_f32_dpp v160, v132, v132 row_half_mirror row_mask:0xf bank_mask:0xf
	v_add_f32_e32 v133, v128, v129
	s_waitcnt vmcnt(31)
	v_cvt_pk_f32_fp8_e32 v[214:215], v48
	v_cvt_pk_f32_fp8_sdwa v[216:217], v48 src0_sel:WORD_1
	v_cvt_pk_f32_fp8_e32 v[218:219], v49
	v_add_f32_dpp v133, v133, v133 quad_perm:[1,0,3,2] row_mask:0xf bank_mask:0xf
	v_cvt_pk_f32_fp8_sdwa v[220:221], v49 src0_sel:WORD_1
	v_cvt_pk_f32_fp8_e32 v[222:223], v50
	v_cvt_pk_f32_fp8_sdwa v[224:225], v50 src0_sel:WORD_1
	v_cvt_pk_f32_fp8_e32 v[226:227], v51
	v_add_f32_dpp v133, v133, v133 quad_perm:[2,3,0,1] row_mask:0xf bank_mask:0xf
	v_cvt_pk_f32_fp8_sdwa v[228:229], v51 src0_sel:WORD_1
	v_pk_mul_f32 v[128:129], v[214:215], v[182:183]
	v_pk_mul_f32 v[130:131], v[216:217], v[184:185]
	v_pk_fma_f32 v[128:129], v[186:187], v[218:219], v[128:129]
	v_pk_fma_f32 v[130:131], v[188:189], v[220:221], v[130:131]
	v_pk_fma_f32 v[128:129], v[190:191], v[222:223], v[128:129]
	v_pk_fma_f32 v[130:131], v[192:193], v[224:225], v[130:131]
	v_pk_fma_f32 v[128:129], v[194:195], v[226:227], v[128:129]
	v_pk_fma_f32 v[130:131], v[196:197], v[228:229], v[130:131]
	buffer_load_dwordx4 v[48:51], v162, s[16:19], s27 offen sc0
	v_pk_add_f32 v[128:129], v[128:129], v[130:131]
	v_add_f32_dpp v161, v133, v133 row_half_mirror row_mask:0xf bank_mask:0xf
	v_add_f32_e32 v132, v128, v129
	s_waitcnt vmcnt(31)
	v_cvt_pk_f32_fp8_e32 v[214:215], v52
	v_cvt_pk_f32_fp8_sdwa v[216:217], v52 src0_sel:WORD_1
	v_cvt_pk_f32_fp8_e32 v[218:219], v53
	v_add_f32_dpp v132, v132, v132 quad_perm:[1,0,3,2] row_mask:0xf bank_mask:0xf
	v_cvt_pk_f32_fp8_sdwa v[220:221], v53 src0_sel:WORD_1
	v_cvt_pk_f32_fp8_e32 v[222:223], v54
	v_cvt_pk_f32_fp8_sdwa v[224:225], v54 src0_sel:WORD_1
	v_cvt_pk_f32_fp8_e32 v[226:227], v55
	v_add_f32_dpp v132, v132, v132 quad_perm:[2,3,0,1] row_mask:0xf bank_mask:0xf
	v_cvt_pk_f32_fp8_sdwa v[228:229], v55 src0_sel:WORD_1
	v_pk_mul_f32 v[128:129], v[214:215], v[182:183]
	v_pk_mul_f32 v[130:131], v[216:217], v[184:185]
	v_pk_fma_f32 v[128:129], v[186:187], v[218:219], v[128:129]
	v_pk_fma_f32 v[130:131], v[188:189], v[220:221], v[130:131]
	v_pk_fma_f32 v[128:129], v[190:191], v[222:223], v[128:129]
	v_pk_fma_f32 v[130:131], v[192:193], v[224:225], v[130:131]
	v_pk_fma_f32 v[128:129], v[194:195], v[226:227], v[128:129]
	v_pk_fma_f32 v[130:131], v[196:197], v[228:229], v[130:131]
	buffer_load_dwordx4 v[52:55], v163, s[16:19], s27 offen sc0
	v_pk_add_f32 v[128:129], v[128:129], v[130:131]
	v_add_f32_dpp v162, v132, v132 row_half_mirror row_mask:0xf bank_mask:0xf
	v_add_f32_e32 v133, v128, v129
	s_waitcnt vmcnt(31)
	v_cvt_pk_f32_fp8_e32 v[214:215], v56
	v_cvt_pk_f32_fp8_sdwa v[216:217], v56 src0_sel:WORD_1
	v_cvt_pk_f32_fp8_e32 v[218:219], v57
	v_add_f32_dpp v133, v133, v133 quad_perm:[1,0,3,2] row_mask:0xf bank_mask:0xf
	v_cvt_pk_f32_fp8_sdwa v[220:221], v57 src0_sel:WORD_1
	v_cvt_pk_f32_fp8_e32 v[222:223], v58
	v_cvt_pk_f32_fp8_sdwa v[224:225], v58 src0_sel:WORD_1
	v_cvt_pk_f32_fp8_e32 v[226:227], v59
	v_add_f32_dpp v133, v133, v133 quad_perm:[2,3,0,1] row_mask:0xf bank_mask:0xf
	v_cvt_pk_f32_fp8_sdwa v[228:229], v59 src0_sel:WORD_1
	v_pk_mul_f32 v[128:129], v[214:215], v[182:183]
	v_pk_mul_f32 v[130:131], v[216:217], v[184:185]
	v_pk_fma_f32 v[128:129], v[186:187], v[218:219], v[128:129]
	v_pk_fma_f32 v[130:131], v[188:189], v[220:221], v[130:131]
	v_pk_fma_f32 v[128:129], v[190:191], v[222:223], v[128:129]
	v_pk_fma_f32 v[130:131], v[192:193], v[224:225], v[130:131]
	v_pk_fma_f32 v[128:129], v[194:195], v[226:227], v[128:129]
	v_pk_fma_f32 v[130:131], v[196:197], v[228:229], v[130:131]
	buffer_load_dwordx4 v[56:59], v164, s[16:19], s27 offen sc0
	v_pk_add_f32 v[128:129], v[128:129], v[130:131]
	v_add_f32_dpp v163, v133, v133 row_half_mirror row_mask:0xf bank_mask:0xf
	v_add_f32_e32 v132, v128, v129
	s_waitcnt vmcnt(31)
; #define LAS __attribute__((address_space(3)))
; __device__ __forceinline__ float red8(float v) { v += dpp_f<0xB1>(v); v += dpp_f<0x4E>(v); v += dpp_f<0x141>(v); return v; }
; __device__ __forceinline__ void kv8_issue(u32x4 (&buf)[8], __amdgpu_buffer_rsrc_t rs, int voff  , int sbase  , const int (&iv)[4], int b) {
;     const int jj = b >> 3, l0 = (b & 7) * 8;
;     const int ivb = (jj == 0) ? iv[0] : (jj == 1) ? iv[1] : (jj == 2) ? iv[2] : iv[3];
; #pragma unroll
;     for (int u = 0; u < 8; ++u) { const int si = __builtin_amdgcn_readlane(ivb, l0 + u); buf[u] = __builtin_amdgcn_raw_buffer_load_b128(rs, voff, si * 2048 + sbase, KV8_AUX); }
; __device__ __forceinline__ void kv8_qk(const u32x4 (&buf)[8], const f32x2v (&q2)[8], LAS float* srow, int b, int lane) {
; #pragma unroll
;     for (int u = 0; u < 8; ++u) {
;         const u32x4 k = buf[u];
;         f32x2v s0 = q2[0] * __builtin_amdgcn_cvt_pk_f32_fp8(k.x, false), s1 = q2[1] * __builtin_amdgcn_cvt_pk_f32_fp8(k.x, true);
;         s0 = __builtin_elementwise_fma(q2[2], __builtin_amdgcn_cvt_pk_f32_fp8(k.y, false), s0); s1 = __builtin_elementwise_fma(q2[3], __builtin_amdgcn_cvt_pk_f32_fp8(k.y, true), s1);
;         s0 = __builtin_elementwise_fma(q2[4], __builtin_amdgcn_cvt_pk_f32_fp8(k.z, false), s0); s1 = __builtin_elementwise_fma(q2[5], __builtin_amdgcn_cvt_pk_f32_fp8(k.z, true), s1);
;         s0 = __builtin_elementwise_fma(q2[6], __builtin_amdgcn_cvt_pk_f32_fp8(k.w, false), s0); s1 = __builtin_elementwise_fma(q2[7], __builtin_amdgcn_cvt_pk_f32_fp8(k.w, true), s1);
;         const f32x2v t = s0 + s1;
;         const float s = red8(t.x + t.y);
;         if ((lane & 7) == 0) srow[b * 8 + u] = s;
;     }
	v_cvt_pk_f32_fp8_e32 v[214:215], v60
	v_cvt_pk_f32_fp8_sdwa v[216:217], v60 src0_sel:WORD_1
	v_cvt_pk_f32_fp8_e32 v[218:219], v61
	v_add_f32_dpp v132, v132, v132 quad_perm:[1,0,3,2] row_mask:0xf bank_mask:0xf
	v_cvt_pk_f32_fp8_sdwa v[220:221], v61 src0_sel:WORD_1
	v_cvt_pk_f32_fp8_e32 v[222:223], v62
	v_cvt_pk_f32_fp8_sdwa v[224:225], v62 src0_sel:WORD_1
	v_cvt_pk_f32_fp8_e32 v[226:227], v63
	v_add_f32_dpp v132, v132, v132 quad_perm:[2,3,0,1] row_mask:0xf bank_mask:0xf
	v_cvt_pk_f32_fp8_sdwa v[228:229], v63 src0_sel:WORD_1
	v_pk_mul_f32 v[128:129], v[214:215], v[182:183]
	v_pk_mul_f32 v[130:131], v[216:217], v[184:185]
	v_pk_fma_f32 v[128:129], v[186:187], v[218:219], v[128:129]
	v_pk_fma_f32 v[130:131], v[188:189], v[220:221], v[130:131]
	v_pk_fma_f32 v[128:129], v[190:191], v[222:223], v[128:129]
	v_pk_fma_f32 v[130:131], v[192:193], v[224:225], v[130:131]
	v_pk_fma_f32 v[128:129], v[194:195], v[226:227], v[128:129]
	v_pk_fma_f32 v[130:131], v[196:197], v[228:229], v[130:131]
	buffer_load_dwordx4 v[60:63], v165, s[16:19], s27 offen sc0
	v_pk_add_f32 v[128:129], v[128:129], v[130:131]
	v_add_f32_dpp v164, v132, v132 row_half_mirror row_mask:0xf bank_mask:0xf
	v_add_f32_e32 v133, v128, v129
	s_waitcnt vmcnt(31)
	v_cvt_pk_f32_fp8_e32 v[214:215], v64
	v_cvt_pk_f32_fp8_sdwa v[216:217], v64 src0_sel:WORD_1
	v_cvt_pk_f32_fp8_e32 v[218:219], v65
	v_add_f32_dpp v133, v133, v133 quad_perm:[1,0,3,2] row_mask:0xf bank_mask:0xf
	v_cvt_pk_f32_fp8_sdwa v[220:221], v65 src0_sel:WORD_1
	v_cvt_pk_f32_fp8_e32 v[222:223], v66
	v_cvt_pk_f32_fp8_sdwa v[224:225], v66 src0_sel:WORD_1
	v_cvt_pk_f32_fp8_e32 v[226:227], v67
	v_add_f32_dpp v133, v133, v133 quad_perm:[2,3,0,1] row_mask:0xf bank_mask:0xf
	v_cvt_pk_f32_fp8_sdwa v[228:229], v67 src0_sel:WORD_1
	v_pk_mul_f32 v[128:129], v[214:215], v[182:183]
	v_pk_mul_f32 v[130:131], v[216:217], v[184:185]
	v_pk_fma_f32 v[128:129], v[186:187], v[218:219], v[128:129]
	v_pk_fma_f32 v[130:131], v[188:189], v[220:221], v[130:131]
	v_pk_fma_f32 v[128:129], v[190:191], v[222:223], v[128:129]
	v_pk_fma_f32 v[130:131], v[192:193], v[224:225], v[130:131]
	v_pk_fma_f32 v[128:129], v[194:195], v[226:227], v[128:129]
	v_pk_fma_f32 v[130:131], v[196:197], v[228:229], v[130:131]
	buffer_load_dwordx4 v[64:67], v166, s[16:19], s27 offen sc0
	v_pk_add_f32 v[128:129], v[128:129], v[130:131]
	v_add_f32_dpp v165, v133, v133 row_half_mirror row_mask:0xf bank_mask:0xf
	v_add_f32_e32 v132, v128, v129
	s_waitcnt vmcnt(31)
	v_cvt_pk_f32_fp8_e32 v[214:215], v68
	v_cvt_pk_f32_fp8_sdwa v[216:217], v68 src0_sel:WORD_1
	v_cvt_pk_f32_fp8_e32 v[218:219], v69
	v_add_f32_dpp v132, v132, v132 quad_perm:[1,0,3,2] row_mask:0xf bank_mask:0xf
	v_cvt_pk_f32_fp8_sdwa v[220:221], v69 src0_sel:WORD_1
	v_cvt_pk_f32_fp8_e32 v[222:223], v70
	v_cvt_pk_f32_fp8_sdwa v[224:225], v70 src0_sel:WORD_1
	v_cvt_pk_f32_fp8_e32 v[226:227], v71
	v_add_f32_dpp v132, v132, v132 quad_perm:[2,3,0,1] row_mask:0xf bank_mask:0xf
	v_cvt_pk_f32_fp8_sdwa v[228:229], v71 src0_sel:WORD_1
	v_pk_mul_f32 v[128:129], v[214:215], v[182:183]
	v_pk_mul_f32 v[130:131], v[216:217], v[184:185]
	v_pk_fma_f32 v[128:129], v[186:187], v[218:219], v[128:129]
	v_pk_fma_f32 v[130:131], v[188:189], v[220:221], v[130:131]
	v_pk_fma_f32 v[128:129], v[190:191], v[222:223], v[128:129]
	v_pk_fma_f32 v[130:131], v[192:193], v[224:225], v[130:131]
	v_pk_fma_f32 v[128:129], v[194:195], v[226:227], v[128:129]
	v_pk_fma_f32 v[130:131], v[196:197], v[228:229], v[130:131]
	buffer_load_dwordx4 v[68:71], v167, s[16:19], s27 offen sc0
	v_pk_add_f32 v[128:129], v[128:129], v[130:131]
	v_add_f32_dpp v166, v132, v132 row_half_mirror row_mask:0xf bank_mask:0xf
	v_add_f32_e32 v133, v128, v129
	s_waitcnt vmcnt(31)
	v_cvt_pk_f32_fp8_e32 v[214:215], v72
	v_cvt_pk_f32_fp8_sdwa v[216:217], v72 src0_sel:WORD_1
	v_cvt_pk_f32_fp8_e32 v[218:219], v73
	v_add_f32_dpp v133, v133, v133 quad_perm:[1,0,3,2] row_mask:0xf bank_mask:0xf
	v_cvt_pk_f32_fp8_sdwa v[220:221], v73 src0_sel:WORD_1
	v_cvt_pk_f32_fp8_e32 v[222:223], v74
	v_cvt_pk_f32_fp8_sdwa v[224:225], v74 src0_sel:WORD_1
	v_cvt_pk_f32_fp8_e32 v[226:227], v75
	v_add_f32_dpp v133, v133, v133 quad_perm:[2,3,0,1] row_mask:0xf bank_mask:0xf
	v_cvt_pk_f32_fp8_sdwa v[228:229], v75 src0_sel:WORD_1
	v_pk_mul_f32 v[128:129], v[214:215], v[182:183]
	v_pk_mul_f32 v[130:131], v[216:217], v[184:185]
	v_pk_fma_f32 v[128:129], v[186:187], v[218:219], v[128:129]
	v_pk_fma_f32 v[130:131], v[188:189], v[220:221], v[130:131]
	v_pk_fma_f32 v[128:129], v[190:191], v[222:223], v[128:129]
	v_pk_fma_f32 v[130:131], v[192:193], v[224:225], v[130:131]
	v_pk_fma_f32 v[128:129], v[194:195], v[226:227], v[128:129]
	v_pk_fma_f32 v[130:131], v[196:197], v[228:229], v[130:131]
	buffer_load_dwordx4 v[72:75], v168, s[16:19], s27 offen sc0
	v_pk_add_f32 v[128:129], v[128:129], v[130:131]
	v_add_f32_dpp v167, v133, v133 row_half_mirror row_mask:0xf bank_mask:0xf
	v_add_f32_e32 v132, v128, v129
	s_waitcnt vmcnt(31)
	v_cvt_pk_f32_fp8_e32 v[214:215], v76
	v_cvt_pk_f32_fp8_sdwa v[216:217], v76 src0_sel:WORD_1
	v_cvt_pk_f32_fp8_e32 v[218:219], v77
	v_add_f32_dpp v132, v132, v132 quad_perm:[1,0,3,2] row_mask:0xf bank_mask:0xf
	v_cvt_pk_f32_fp8_sdwa v[220:221], v77 src0_sel:WORD_1
	v_cvt_pk_f32_fp8_e32 v[222:223], v78
	v_cvt_pk_f32_fp8_sdwa v[224:225], v78 src0_sel:WORD_1
	v_cvt_pk_f32_fp8_e32 v[226:227], v79
	v_add_f32_dpp v132, v132, v132 quad_perm:[2,3,0,1] row_mask:0xf bank_mask:0xf
	v_cvt_pk_f32_fp8_sdwa v[228:229], v79 src0_sel:WORD_1
	v_pk_mul_f32 v[128:129], v[214:215], v[182:183]
	v_pk_mul_f32 v[130:131], v[216:217], v[184:185]
	v_pk_fma_f32 v[128:129], v[186:187], v[218:219], v[128:129]
	v_pk_fma_f32 v[130:131], v[188:189], v[220:221], v[130:131]
	v_pk_fma_f32 v[128:129], v[190:191], v[222:223], v[128:129]
	v_pk_fma_f32 v[130:131], v[192:193], v[224:225], v[130:131]
	v_pk_fma_f32 v[128:129], v[194:195], v[226:227], v[128:129]
	v_pk_fma_f32 v[130:131], v[196:197], v[228:229], v[130:131]
	buffer_load_dwordx4 v[76:79], v169, s[16:19], s27 offen sc0
	v_pk_add_f32 v[128:129], v[128:129], v[130:131]
	v_add_f32_dpp v168, v132, v132 row_half_mirror row_mask:0xf bank_mask:0xf
	v_add_f32_e32 v133, v128, v129
	s_waitcnt vmcnt(31)
; #define LAS __attribute__((address_space(3)))
; __device__ __forceinline__ float red8(float v) { v += dpp_f<0xB1>(v); v += dpp_f<0x4E>(v); v += dpp_f<0x141>(v); return v; }
; __device__ __forceinline__ void kv8_issue(u32x4 (&buf)[8], __amdgpu_buffer_rsrc_t rs, int voff  , int sbase  , const int (&iv)[4], int b) {
;     const int jj = b >> 3, l0 = (b & 7) * 8;
;     const int ivb = (jj == 0) ? iv[0] : (jj == 1) ? iv[1] : (jj == 2) ? iv[2] : iv[3];
; #pragma unroll
;     for (int u = 0; u < 8; ++u) { const int si = __builtin_amdgcn_readlane(ivb, l0 + u); buf[u] = __builtin_amdgcn_raw_buffer_load_b128(rs, voff, si * 2048 + sbase, KV8_AUX); }
; __device__ __forceinline__ void kv8_qk(const u32x4 (&buf)[8], const f32x2v (&q2)[8], LAS float* srow, int b, int lane) {
; #pragma unroll
;     for (int u = 0; u < 8; ++u) {
;         const u32x4 k = buf[u];
;         f32x2v s0 = q2[0] * __builtin_amdgcn_cvt_pk_f32_fp8(k.x, false), s1 = q2[1] * __builtin_amdgcn_cvt_pk_f32_fp8(k.x, true);
;         s0 = __builtin_elementwise_fma(q2[2], __builtin_amdgcn_cvt_pk_f32_fp8(k.y, false), s0); s1 = __builtin_elementwise_fma(q2[3], __builtin_amdgcn_cvt_pk_f32_fp8(k.y, true), s1);
;         s0 = __builtin_elementwise_fma(q2[4], __builtin_amdgcn_cvt_pk_f32_fp8(k.z, false), s0); s1 = __builtin_elementwise_fma(q2[5], __builtin_amdgcn_cvt_pk_f32_fp8(k.z, true), s1);
;         s0 = __builtin_elementwise_fma(q2[6], __builtin_amdgcn_cvt_pk_f32_fp8(k.w, false), s0); s1 = __builtin_elementwise_fma(q2[7], __builtin_amdgcn_cvt_pk_f32_fp8(k.w, true), s1);
;         const f32x2v t = s0 + s1;
;         const float s = red8(t.x + t.y);
;         if ((lane & 7) == 0) srow[b * 8 + u] = s;
;     }
	v_cvt_pk_f32_fp8_e32 v[214:215], v80
	v_cvt_pk_f32_fp8_sdwa v[216:217], v80 src0_sel:WORD_1
	v_cvt_pk_f32_fp8_e32 v[218:219], v81
	v_add_f32_dpp v133, v133, v133 quad_perm:[1,0,3,2] row_mask:0xf bank_mask:0xf
	v_cvt_pk_f32_fp8_sdwa v[220:221], v81 src0_sel:WORD_1
	v_cvt_pk_f32_fp8_e32 v[222:223], v82
	v_cvt_pk_f32_fp8_sdwa v[224:225], v82 src0_sel:WORD_1
	v_cvt_pk_f32_fp8_e32 v[226:227], v83
	v_add_f32_dpp v133, v133, v133 quad_perm:[2,3,0,1] row_mask:0xf bank_mask:0xf
	v_cvt_pk_f32_fp8_sdwa v[228:229], v83 src0_sel:WORD_1
	v_pk_mul_f32 v[128:129], v[214:215], v[182:183]
	v_pk_mul_f32 v[130:131], v[216:217], v[184:185]
	v_pk_fma_f32 v[128:129], v[186:187], v[218:219], v[128:129]
	v_pk_fma_f32 v[130:131], v[188:189], v[220:221], v[130:131]
	v_pk_fma_f32 v[128:129], v[190:191], v[222:223], v[128:129]
	v_pk_fma_f32 v[130:131], v[192:193], v[224:225], v[130:131]
	v_pk_fma_f32 v[128:129], v[194:195], v[226:227], v[128:129]
	v_pk_fma_f32 v[130:131], v[196:197], v[228:229], v[130:131]
	buffer_load_dwordx4 v[80:83], v170, s[16:19], s27 offen sc0
	v_pk_add_f32 v[128:129], v[128:129], v[130:131]
	v_add_f32_dpp v169, v133, v133 row_half_mirror row_mask:0xf bank_mask:0xf
	v_add_f32_e32 v132, v128, v129
	s_waitcnt vmcnt(31)
	v_cvt_pk_f32_fp8_e32 v[214:215], v84
	v_cvt_pk_f32_fp8_sdwa v[216:217], v84 src0_sel:WORD_1
	v_cvt_pk_f32_fp8_e32 v[218:219], v85
	v_add_f32_dpp v132, v132, v132 quad_perm:[1,0,3,2] row_mask:0xf bank_mask:0xf
	v_cvt_pk_f32_fp8_sdwa v[220:221], v85 src0_sel:WORD_1
	v_cvt_pk_f32_fp8_e32 v[222:223], v86
	v_cvt_pk_f32_fp8_sdwa v[224:225], v86 src0_sel:WORD_1
	v_cvt_pk_f32_fp8_e32 v[226:227], v87
	v_add_f32_dpp v132, v132, v132 quad_perm:[2,3,0,1] row_mask:0xf bank_mask:0xf
	v_cvt_pk_f32_fp8_sdwa v[228:229], v87 src0_sel:WORD_1
	v_pk_mul_f32 v[128:129], v[214:215], v[182:183]
	v_pk_mul_f32 v[130:131], v[216:217], v[184:185]
	v_pk_fma_f32 v[128:129], v[186:187], v[218:219], v[128:129]
	v_pk_fma_f32 v[130:131], v[188:189], v[220:221], v[130:131]
	v_pk_fma_f32 v[128:129], v[190:191], v[222:223], v[128:129]
	v_pk_fma_f32 v[130:131], v[192:193], v[224:225], v[130:131]
	v_pk_fma_f32 v[128:129], v[194:195], v[226:227], v[128:129]
	v_pk_fma_f32 v[130:131], v[196:197], v[228:229], v[130:131]
	buffer_load_dwordx4 v[84:87], v171, s[16:19], s27 offen sc0
	v_pk_add_f32 v[128:129], v[128:129], v[130:131]
	v_add_f32_dpp v170, v132, v132 row_half_mirror row_mask:0xf bank_mask:0xf
	v_add_f32_e32 v133, v128, v129
	s_waitcnt vmcnt(31)
	v_cvt_pk_f32_fp8_e32 v[214:215], v88
	v_cvt_pk_f32_fp8_sdwa v[216:217], v88 src0_sel:WORD_1
	v_cvt_pk_f32_fp8_e32 v[218:219], v89
	v_add_f32_dpp v133, v133, v133 quad_perm:[1,0,3,2] row_mask:0xf bank_mask:0xf
	v_cvt_pk_f32_fp8_sdwa v[220:221], v89 src0_sel:WORD_1
	v_cvt_pk_f32_fp8_e32 v[222:223], v90
	v_cvt_pk_f32_fp8_sdwa v[224:225], v90 src0_sel:WORD_1
	v_cvt_pk_f32_fp8_e32 v[226:227], v91
	v_add_f32_dpp v133, v133, v133 quad_perm:[2,3,0,1] row_mask:0xf bank_mask:0xf
	v_cvt_pk_f32_fp8_sdwa v[228:229], v91 src0_sel:WORD_1
	v_pk_mul_f32 v[128:129], v[214:215], v[182:183]
	v_pk_mul_f32 v[130:131], v[216:217], v[184:185]
	v_pk_fma_f32 v[128:129], v[186:187], v[218:219], v[128:129]
	v_pk_fma_f32 v[130:131], v[188:189], v[220:221], v[130:131]
	v_pk_fma_f32 v[128:129], v[190:191], v[222:223], v[128:129]
	v_pk_fma_f32 v[130:131], v[192:193], v[224:225], v[130:131]
	v_pk_fma_f32 v[128:129], v[194:195], v[226:227], v[128:129]
	v_pk_fma_f32 v[130:131], v[196:197], v[228:229], v[130:131]
	buffer_load_dwordx4 v[88:91], v172, s[16:19], s27 offen sc0
	v_pk_add_f32 v[128:129], v[128:129], v[130:131]
	v_add_f32_dpp v171, v133, v133 row_half_mirror row_mask:0xf bank_mask:0xf
	v_add_f32_e32 v132, v128, v129
	s_waitcnt vmcnt(31)
	v_cvt_pk_f32_fp8_e32 v[214:215], v92
	v_cvt_pk_f32_fp8_sdwa v[216:217], v92 src0_sel:WORD_1
	v_cvt_pk_f32_fp8_e32 v[218:219], v93
	v_add_f32_dpp v132, v132, v132 quad_perm:[1,0,3,2] row_mask:0xf bank_mask:0xf
	v_cvt_pk_f32_fp8_sdwa v[220:221], v93 src0_sel:WORD_1
	v_cvt_pk_f32_fp8_e32 v[222:223], v94
	v_cvt_pk_f32_fp8_sdwa v[224:225], v94 src0_sel:WORD_1
	v_cvt_pk_f32_fp8_e32 v[226:227], v95
	v_add_f32_dpp v132, v132, v132 quad_perm:[2,3,0,1] row_mask:0xf bank_mask:0xf
	v_cvt_pk_f32_fp8_sdwa v[228:229], v95 src0_sel:WORD_1
	v_pk_mul_f32 v[128:129], v[214:215], v[182:183]
	v_pk_mul_f32 v[130:131], v[216:217], v[184:185]
	v_pk_fma_f32 v[128:129], v[186:187], v[218:219], v[128:129]
	v_pk_fma_f32 v[130:131], v[188:189], v[220:221], v[130:131]
	v_pk_fma_f32 v[128:129], v[190:191], v[222:223], v[128:129]
	v_pk_fma_f32 v[130:131], v[192:193], v[224:225], v[130:131]
	v_pk_fma_f32 v[128:129], v[194:195], v[226:227], v[128:129]
	v_pk_fma_f32 v[130:131], v[196:197], v[228:229], v[130:131]
	buffer_load_dwordx4 v[92:95], v173, s[16:19], s27 offen sc0
	v_pk_add_f32 v[128:129], v[128:129], v[130:131]
	v_add_f32_dpp v172, v132, v132 row_half_mirror row_mask:0xf bank_mask:0xf
	v_add_f32_e32 v133, v128, v129
	s_waitcnt vmcnt(31)
	v_cvt_pk_f32_fp8_e32 v[214:215], v96
	v_cvt_pk_f32_fp8_sdwa v[216:217], v96 src0_sel:WORD_1
	v_cvt_pk_f32_fp8_e32 v[218:219], v97
	v_add_f32_dpp v133, v133, v133 quad_perm:[1,0,3,2] row_mask:0xf bank_mask:0xf
	v_cvt_pk_f32_fp8_sdwa v[220:221], v97 src0_sel:WORD_1
	v_cvt_pk_f32_fp8_e32 v[222:223], v98
	v_cvt_pk_f32_fp8_sdwa v[224:225], v98 src0_sel:WORD_1
	v_cvt_pk_f32_fp8_e32 v[226:227], v99
	v_add_f32_dpp v133, v133, v133 quad_perm:[2,3,0,1] row_mask:0xf bank_mask:0xf
	v_cvt_pk_f32_fp8_sdwa v[228:229], v99 src0_sel:WORD_1
	v_pk_mul_f32 v[128:129], v[214:215], v[182:183]
	v_pk_mul_f32 v[130:131], v[216:217], v[184:185]
	v_pk_fma_f32 v[128:129], v[186:187], v[218:219], v[128:129]
	v_pk_fma_f32 v[130:131], v[188:189], v[220:221], v[130:131]
	v_pk_fma_f32 v[128:129], v[190:191], v[222:223], v[128:129]
	v_pk_fma_f32 v[130:131], v[192:193], v[224:225], v[130:131]
	v_pk_fma_f32 v[128:129], v[194:195], v[226:227], v[128:129]
	v_pk_fma_f32 v[130:131], v[196:197], v[228:229], v[130:131]
	buffer_load_dwordx4 v[96:99], v174, s[16:19], s27 offen sc0
	v_pk_add_f32 v[128:129], v[128:129], v[130:131]
	v_add_f32_dpp v173, v133, v133 row_half_mirror row_mask:0xf bank_mask:0xf
	v_add_f32_e32 v132, v128, v129
	s_waitcnt vmcnt(31)
; #define LAS __attribute__((address_space(3)))
; __device__ __forceinline__ float red8(float v) { v += dpp_f<0xB1>(v); v += dpp_f<0x4E>(v); v += dpp_f<0x141>(v); return v; }
; __device__ __forceinline__ void kv8_issue(u32x4 (&buf)[8], __amdgpu_buffer_rsrc_t rs, int voff  , int sbase  , const int (&iv)[4], int b) {
;     const int jj = b >> 3, l0 = (b & 7) * 8;
;     const int ivb = (jj == 0) ? iv[0] : (jj == 1) ? iv[1] : (jj == 2) ? iv[2] : iv[3];
; #pragma unroll
;     for (int u = 0; u < 8; ++u) { const int si = __builtin_amdgcn_readlane(ivb, l0 + u); buf[u] = __builtin_amdgcn_raw_buffer_load_b128(rs, voff, si * 2048 + sbase, KV8_AUX); }
; __device__ __forceinline__ void kv8_qk(const u32x4 (&buf)[8], const f32x2v (&q2)[8], LAS float* srow, int b, int lane) {
; #pragma unroll
;     for (int u = 0; u < 8; ++u) {
;         const u32x4 k = buf[u];
;         f32x2v s0 = q2[0] * __builtin_amdgcn_cvt_pk_f32_fp8(k.x, false), s1 = q2[1] * __builtin_amdgcn_cvt_pk_f32_fp8(k.x, true);
;         s0 = __builtin_elementwise_fma(q2[2], __builtin_amdgcn_cvt_pk_f32_fp8(k.y, false), s0); s1 = __builtin_elementwise_fma(q2[3], __builtin_amdgcn_cvt_pk_f32_fp8(k.y, true), s1);
;         s0 = __builtin_elementwise_fma(q2[4], __builtin_amdgcn_cvt_pk_f32_fp8(k.z, false), s0); s1 = __builtin_elementwise_fma(q2[5], __builtin_amdgcn_cvt_pk_f32_fp8(k.z, true), s1);
;         s0 = __builtin_elementwise_fma(q2[6], __builtin_amdgcn_cvt_pk_f32_fp8(k.w, false), s0); s1 = __builtin_elementwise_fma(q2[7], __builtin_amdgcn_cvt_pk_f32_fp8(k.w, true), s1);
;         const f32x2v t = s0 + s1;
;         const float s = red8(t.x + t.y);
;         if ((lane & 7) == 0) srow[b * 8 + u] = s;
;     }
	v_cvt_pk_f32_fp8_e32 v[214:215], v100
	v_cvt_pk_f32_fp8_sdwa v[216:217], v100 src0_sel:WORD_1
	v_cvt_pk_f32_fp8_e32 v[218:219], v101
	v_add_f32_dpp v132, v132, v132 quad_perm:[1,0,3,2] row_mask:0xf bank_mask:0xf
	v_cvt_pk_f32_fp8_sdwa v[220:221], v101 src0_sel:WORD_1
	v_cvt_pk_f32_fp8_e32 v[222:223], v102
	v_cvt_pk_f32_fp8_sdwa v[224:225], v102 src0_sel:WORD_1
	v_cvt_pk_f32_fp8_e32 v[226:227], v103
	v_add_f32_dpp v132, v132, v132 quad_perm:[2,3,0,1] row_mask:0xf bank_mask:0xf
	v_cvt_pk_f32_fp8_sdwa v[228:229], v103 src0_sel:WORD_1
	v_pk_mul_f32 v[128:129], v[214:215], v[182:183]
	v_pk_mul_f32 v[130:131], v[216:217], v[184:185]
	v_pk_fma_f32 v[128:129], v[186:187], v[218:219], v[128:129]
	v_pk_fma_f32 v[130:131], v[188:189], v[220:221], v[130:131]
	v_pk_fma_f32 v[128:129], v[190:191], v[222:223], v[128:129]
	v_pk_fma_f32 v[130:131], v[192:193], v[224:225], v[130:131]
	v_pk_fma_f32 v[128:129], v[194:195], v[226:227], v[128:129]
	v_pk_fma_f32 v[130:131], v[196:197], v[228:229], v[130:131]
	buffer_load_dwordx4 v[100:103], v175, s[16:19], s27 offen sc0
	v_pk_add_f32 v[128:129], v[128:129], v[130:131]
	v_add_f32_dpp v174, v132, v132 row_half_mirror row_mask:0xf bank_mask:0xf
	v_add_f32_e32 v133, v128, v129
	s_waitcnt vmcnt(31)
	v_cvt_pk_f32_fp8_e32 v[214:215], v104
	v_cvt_pk_f32_fp8_sdwa v[216:217], v104 src0_sel:WORD_1
	v_cvt_pk_f32_fp8_e32 v[218:219], v105
	v_add_f32_dpp v133, v133, v133 quad_perm:[1,0,3,2] row_mask:0xf bank_mask:0xf
	v_cvt_pk_f32_fp8_sdwa v[220:221], v105 src0_sel:WORD_1
	v_cvt_pk_f32_fp8_e32 v[222:223], v106
	v_cvt_pk_f32_fp8_sdwa v[224:225], v106 src0_sel:WORD_1
	v_cvt_pk_f32_fp8_e32 v[226:227], v107
	v_add_f32_dpp v133, v133, v133 quad_perm:[2,3,0,1] row_mask:0xf bank_mask:0xf
	v_cvt_pk_f32_fp8_sdwa v[228:229], v107 src0_sel:WORD_1
	v_pk_mul_f32 v[128:129], v[214:215], v[182:183]
	v_pk_mul_f32 v[130:131], v[216:217], v[184:185]
	v_pk_fma_f32 v[128:129], v[186:187], v[218:219], v[128:129]
	v_pk_fma_f32 v[130:131], v[188:189], v[220:221], v[130:131]
	v_pk_fma_f32 v[128:129], v[190:191], v[222:223], v[128:129]
	v_pk_fma_f32 v[130:131], v[192:193], v[224:225], v[130:131]
	v_pk_fma_f32 v[128:129], v[194:195], v[226:227], v[128:129]
	v_pk_fma_f32 v[130:131], v[196:197], v[228:229], v[130:131]
	buffer_load_dwordx4 v[104:107], v176, s[16:19], s27 offen sc0
	v_pk_add_f32 v[128:129], v[128:129], v[130:131]
	v_add_f32_dpp v175, v133, v133 row_half_mirror row_mask:0xf bank_mask:0xf
	v_add_f32_e32 v132, v128, v129
	s_waitcnt vmcnt(31)
	v_cvt_pk_f32_fp8_e32 v[214:215], v108
	v_cvt_pk_f32_fp8_sdwa v[216:217], v108 src0_sel:WORD_1
	v_cvt_pk_f32_fp8_e32 v[218:219], v109
	v_add_f32_dpp v132, v132, v132 quad_perm:[1,0,3,2] row_mask:0xf bank_mask:0xf
	v_cvt_pk_f32_fp8_sdwa v[220:221], v109 src0_sel:WORD_1
	v_cvt_pk_f32_fp8_e32 v[222:223], v110
	v_cvt_pk_f32_fp8_sdwa v[224:225], v110 src0_sel:WORD_1
	v_cvt_pk_f32_fp8_e32 v[226:227], v111
	v_add_f32_dpp v132, v132, v132 quad_perm:[2,3,0,1] row_mask:0xf bank_mask:0xf
	v_cvt_pk_f32_fp8_sdwa v[228:229], v111 src0_sel:WORD_1
	v_pk_mul_f32 v[128:129], v[214:215], v[182:183]
	v_pk_mul_f32 v[130:131], v[216:217], v[184:185]
	v_pk_fma_f32 v[128:129], v[186:187], v[218:219], v[128:129]
	v_pk_fma_f32 v[130:131], v[188:189], v[220:221], v[130:131]
	v_pk_fma_f32 v[128:129], v[190:191], v[222:223], v[128:129]
	v_pk_fma_f32 v[130:131], v[192:193], v[224:225], v[130:131]
	v_pk_fma_f32 v[128:129], v[194:195], v[226:227], v[128:129]
	v_pk_fma_f32 v[130:131], v[196:197], v[228:229], v[130:131]
	buffer_load_dwordx4 v[108:111], v177, s[16:19], s27 offen sc0
	v_pk_add_f32 v[128:129], v[128:129], v[130:131]
	v_add_f32_dpp v176, v132, v132 row_half_mirror row_mask:0xf bank_mask:0xf
	v_add_f32_e32 v133, v128, v129
	s_waitcnt vmcnt(31)
	v_cvt_pk_f32_fp8_e32 v[214:215], v112
	v_cvt_pk_f32_fp8_sdwa v[216:217], v112 src0_sel:WORD_1
	v_cvt_pk_f32_fp8_e32 v[218:219], v113
	v_add_f32_dpp v133, v133, v133 quad_perm:[1,0,3,2] row_mask:0xf bank_mask:0xf
	v_cvt_pk_f32_fp8_sdwa v[220:221], v113 src0_sel:WORD_1
	v_cvt_pk_f32_fp8_e32 v[222:223], v114
	v_cvt_pk_f32_fp8_sdwa v[224:225], v114 src0_sel:WORD_1
	v_cvt_pk_f32_fp8_e32 v[226:227], v115
	v_add_f32_dpp v133, v133, v133 quad_perm:[2,3,0,1] row_mask:0xf bank_mask:0xf
	v_cvt_pk_f32_fp8_sdwa v[228:229], v115 src0_sel:WORD_1
	v_pk_mul_f32 v[128:129], v[214:215], v[182:183]
	v_pk_mul_f32 v[130:131], v[216:217], v[184:185]
	v_pk_fma_f32 v[128:129], v[186:187], v[218:219], v[128:129]
	v_pk_fma_f32 v[130:131], v[188:189], v[220:221], v[130:131]
	v_pk_fma_f32 v[128:129], v[190:191], v[222:223], v[128:129]
	v_pk_fma_f32 v[130:131], v[192:193], v[224:225], v[130:131]
	v_pk_fma_f32 v[128:129], v[194:195], v[226:227], v[128:129]
	v_pk_fma_f32 v[130:131], v[196:197], v[228:229], v[130:131]
	buffer_load_dwordx4 v[112:115], v178, s[16:19], s27 offen sc0
	v_pk_add_f32 v[128:129], v[128:129], v[130:131]
	v_add_f32_dpp v177, v133, v133 row_half_mirror row_mask:0xf bank_mask:0xf
	v_add_f32_e32 v132, v128, v129
	s_waitcnt vmcnt(31)
	v_cvt_pk_f32_fp8_e32 v[214:215], v116
	v_cvt_pk_f32_fp8_sdwa v[216:217], v116 src0_sel:WORD_1
	v_cvt_pk_f32_fp8_e32 v[218:219], v117
	v_add_f32_dpp v132, v132, v132 quad_perm:[1,0,3,2] row_mask:0xf bank_mask:0xf
	v_cvt_pk_f32_fp8_sdwa v[220:221], v117 src0_sel:WORD_1
	v_cvt_pk_f32_fp8_e32 v[222:223], v118
	v_cvt_pk_f32_fp8_sdwa v[224:225], v118 src0_sel:WORD_1
	v_cvt_pk_f32_fp8_e32 v[226:227], v119
	v_add_f32_dpp v132, v132, v132 quad_perm:[2,3,0,1] row_mask:0xf bank_mask:0xf
	v_cvt_pk_f32_fp8_sdwa v[228:229], v119 src0_sel:WORD_1
	v_pk_mul_f32 v[128:129], v[214:215], v[182:183]
	v_pk_mul_f32 v[130:131], v[216:217], v[184:185]
	v_pk_fma_f32 v[128:129], v[186:187], v[218:219], v[128:129]
	v_pk_fma_f32 v[130:131], v[188:189], v[220:221], v[130:131]
	v_pk_fma_f32 v[128:129], v[190:191], v[222:223], v[128:129]
	v_pk_fma_f32 v[130:131], v[192:193], v[224:225], v[130:131]
	v_pk_fma_f32 v[128:129], v[194:195], v[226:227], v[128:129]
	v_pk_fma_f32 v[130:131], v[196:197], v[228:229], v[130:131]
	buffer_load_dwordx4 v[116:119], v179, s[16:19], s27 offen sc0
	v_pk_add_f32 v[128:129], v[128:129], v[130:131]
	v_add_f32_dpp v178, v132, v132 row_half_mirror row_mask:0xf bank_mask:0xf
	v_add_f32_e32 v133, v128, v129
	s_waitcnt vmcnt(31)
; __device__ __forceinline__ float red8(float v) { v += dpp_f<0xB1>(v); v += dpp_f<0x4E>(v); v += dpp_f<0x141>(v); return v; }
; __device__ __forceinline__ void kv8_qk(const u32x4 (&buf)[8], const f32x2v (&q2)[8], LAS float* srow, int b, int lane) {
;     ...
;     for (int u = 0; u < 8; ++u) {
;         const u32x4 k = buf[u];
;         f32x2v s0 = q2[0] * __builtin_amdgcn_cvt_pk_f32_fp8(k.x, false), s1 = q2[1] * __builtin_amdgcn_cvt_pk_f32_fp8(k.x, true);
;         s0 = __builtin_elementwise_fma(q2[2], __builtin_amdgcn_cvt_pk_f32_fp8(k.y, false), s0); s1 = __builtin_elementwise_fma(q2[3], __builtin_amdgcn_cvt_pk_f32_fp8(k.y, true), s1);
;         s0 = __builtin_elementwise_fma(q2[4], __builtin_amdgcn_cvt_pk_f32_fp8(k.z, false), s0); s1 = __builtin_elementwise_fma(q2[5], __builtin_amdgcn_cvt_pk_f32_fp8(k.z, true), s1);
;         s0 = __builtin_elementwise_fma(q2[6], __builtin_amdgcn_cvt_pk_f32_fp8(k.w, false), s0); s1 = __builtin_elementwise_fma(q2[7], __builtin_amdgcn_cvt_pk_f32_fp8(k.w, true), s1);
;         const f32x2v t = s0 + s1;
;         const float s = red8(t.x + t.y);
;         if ((lane & 7) == 0) srow[b * 8 + u] = s;
;     }
; __device__ __forceinline__ void attn_query8(const unsigned char* __restrict__ KV8, const bf16_t* __restrict__ Z, const int* __restrict__ SEL, bf16_t* __restrict__ YMIX, int t, LAS float* sbuf  ) {
;     ...
;         float sv[4]; float mx = -__builtin_inff();
; #pragma unroll
;         for (int jj = 0; jj < 4; ++jj) { const int j = lane + 64 * jj; const float s = sbuf[h * 256 + j]; sv[jj] = (j < nsel) ? s : -__builtin_inff(); mx = fmaxf(mx, sv[jj]); }
	v_cvt_pk_f32_fp8_e32 v[214:215], v120
	v_cvt_pk_f32_fp8_sdwa v[216:217], v120 src0_sel:WORD_1
	v_cvt_pk_f32_fp8_e32 v[218:219], v121
	v_add_f32_dpp v133, v133, v133 quad_perm:[1,0,3,2] row_mask:0xf bank_mask:0xf
	v_cvt_pk_f32_fp8_sdwa v[220:221], v121 src0_sel:WORD_1
	v_cvt_pk_f32_fp8_e32 v[222:223], v122
	v_cvt_pk_f32_fp8_sdwa v[224:225], v122 src0_sel:WORD_1
	v_cvt_pk_f32_fp8_e32 v[226:227], v123
	v_add_f32_dpp v133, v133, v133 quad_perm:[2,3,0,1] row_mask:0xf bank_mask:0xf
	v_cvt_pk_f32_fp8_sdwa v[228:229], v123 src0_sel:WORD_1
	v_pk_mul_f32 v[128:129], v[214:215], v[182:183]
	v_pk_mul_f32 v[130:131], v[216:217], v[184:185]
	v_pk_fma_f32 v[128:129], v[186:187], v[218:219], v[128:129]
	v_pk_fma_f32 v[130:131], v[188:189], v[220:221], v[130:131]
	v_pk_fma_f32 v[128:129], v[190:191], v[222:223], v[128:129]
	v_pk_fma_f32 v[130:131], v[192:193], v[224:225], v[130:131]
	v_pk_fma_f32 v[128:129], v[194:195], v[226:227], v[128:129]
	v_pk_fma_f32 v[130:131], v[196:197], v[228:229], v[130:131]
	buffer_load_dwordx4 v[120:123], v180, s[16:19], s27 offen sc0
	v_pk_add_f32 v[128:129], v[128:129], v[130:131]
	v_add_f32_dpp v179, v133, v133 row_half_mirror row_mask:0xf bank_mask:0xf
	v_add_f32_e32 v132, v128, v129
	s_waitcnt vmcnt(31)
	v_cvt_pk_f32_fp8_e32 v[214:215], v124
	v_cvt_pk_f32_fp8_sdwa v[216:217], v124 src0_sel:WORD_1
	v_cvt_pk_f32_fp8_e32 v[218:219], v125
	v_add_f32_dpp v132, v132, v132 quad_perm:[1,0,3,2] row_mask:0xf bank_mask:0xf
	v_cvt_pk_f32_fp8_sdwa v[220:221], v125 src0_sel:WORD_1
	v_cvt_pk_f32_fp8_e32 v[222:223], v126
	v_cvt_pk_f32_fp8_sdwa v[224:225], v126 src0_sel:WORD_1
	v_cvt_pk_f32_fp8_e32 v[226:227], v127
	v_add_f32_dpp v132, v132, v132 quad_perm:[2,3,0,1] row_mask:0xf bank_mask:0xf
	v_cvt_pk_f32_fp8_sdwa v[228:229], v127 src0_sel:WORD_1
	v_pk_mul_f32 v[128:129], v[214:215], v[182:183]
	v_pk_mul_f32 v[130:131], v[216:217], v[184:185]
	v_pk_fma_f32 v[128:129], v[186:187], v[218:219], v[128:129]
	v_pk_fma_f32 v[130:131], v[188:189], v[220:221], v[130:131]
	v_pk_fma_f32 v[128:129], v[190:191], v[222:223], v[128:129]
	v_pk_fma_f32 v[130:131], v[192:193], v[224:225], v[130:131]
	v_pk_fma_f32 v[128:129], v[194:195], v[226:227], v[128:129]
	v_pk_fma_f32 v[130:131], v[196:197], v[228:229], v[130:131]
	buffer_load_dwordx4 v[124:127], v181, s[16:19], s27 offen sc0
	v_pk_add_f32 v[128:129], v[128:129], v[130:131]
	v_add_f32_dpp v180, v132, v132 row_half_mirror row_mask:0xf bank_mask:0xf
	v_add_f32_e32 v133, v128, v129
	s_nop 1
	v_add_f32_dpp v133, v133, v133 quad_perm:[1,0,3,2] row_mask:0xf bank_mask:0xf
	s_nop 1
	v_add_f32_dpp v133, v133, v133 quad_perm:[2,3,0,1] row_mask:0xf bank_mask:0xf
	s_nop 1
	v_add_f32_dpp v181, v133, v133 row_half_mirror row_mask:0xf bank_mask:0xf
	s_cmpk_eq_i32 s4, 0x100
	s_cbranch_scc1 .Latt_nomask
	v_cmp_lt_i32_e32 vcc, 0, v143
	s_nop 1
	v_cndmask_b32_e32 v150, v142, v150, vcc
	v_cmp_lt_i32_e32 vcc, 8, v143
	s_nop 1
	v_cndmask_b32_e32 v151, v142, v151, vcc
	v_cmp_lt_i32_e32 vcc, 16, v143
	s_nop 1
	v_cndmask_b32_e32 v152, v142, v152, vcc
	v_cmp_lt_i32_e32 vcc, 24, v143
	s_nop 1
	v_cndmask_b32_e32 v153, v142, v153, vcc
	v_cmp_lt_i32_e32 vcc, 32, v143
	s_nop 1
	v_cndmask_b32_e32 v154, v142, v154, vcc
	v_cmp_lt_i32_e32 vcc, 40, v143
	s_nop 1
	v_cndmask_b32_e32 v155, v142, v155, vcc
	v_cmp_lt_i32_e32 vcc, 48, v143
	s_nop 1
	v_cndmask_b32_e32 v156, v142, v156, vcc
	v_cmp_lt_i32_e32 vcc, 56, v143
	s_nop 1
	v_cndmask_b32_e32 v157, v142, v157, vcc
	v_cmp_lt_i32_e32 vcc, 64, v143
	s_nop 1
	v_cndmask_b32_e32 v158, v142, v158, vcc
	v_cmp_lt_i32_e32 vcc, 0x48, v143
	s_nop 1
	v_cndmask_b32_e32 v159, v142, v159, vcc
	v_cmp_lt_i32_e32 vcc, 0x50, v143
	s_nop 1
	v_cndmask_b32_e32 v160, v142, v160, vcc
	v_cmp_lt_i32_e32 vcc, 0x58, v143
	s_nop 1
	v_cndmask_b32_e32 v161, v142, v161, vcc
	v_cmp_lt_i32_e32 vcc, 0x60, v143
	s_nop 1
	v_cndmask_b32_e32 v162, v142, v162, vcc
	v_cmp_lt_i32_e32 vcc, 0x68, v143
	s_nop 1
	v_cndmask_b32_e32 v163, v142, v163, vcc
	v_cmp_lt_i32_e32 vcc, 0x70, v143
	s_nop 1
	v_cndmask_b32_e32 v164, v142, v164, vcc
	v_cmp_lt_i32_e32 vcc, 0x78, v143
	s_nop 1
	v_cndmask_b32_e32 v165, v142, v165, vcc
	v_cmp_lt_i32_e32 vcc, 0x80, v143
	s_nop 1
	v_cndmask_b32_e32 v166, v142, v166, vcc
	v_cmp_lt_i32_e32 vcc, 0x88, v143
	s_nop 1
	v_cndmask_b32_e32 v167, v142, v167, vcc
	v_cmp_lt_i32_e32 vcc, 0x90, v143
	s_nop 1
	v_cndmask_b32_e32 v168, v142, v168, vcc
	v_cmp_lt_i32_e32 vcc, 0x98, v143
	s_nop 1
	v_cndmask_b32_e32 v169, v142, v169, vcc
	v_cmp_lt_i32_e32 vcc, 0xa0, v143
	s_nop 1
	v_cndmask_b32_e32 v170, v142, v170, vcc
	v_cmp_lt_i32_e32 vcc, 0xa8, v143
	s_nop 1
	v_cndmask_b32_e32 v171, v142, v171, vcc
	v_cmp_lt_i32_e32 vcc, 0xb0, v143
	s_nop 1
	v_cndmask_b32_e32 v172, v142, v172, vcc
	v_cmp_lt_i32_e32 vcc, 0xb8, v143
	s_nop 1
	v_cndmask_b32_e32 v173, v142, v173, vcc
	v_cmp_lt_i32_e32 vcc, 0xc0, v143
	s_nop 1
	v_cndmask_b32_e32 v174, v142, v174, vcc
	v_cmp_lt_i32_e32 vcc, 0xc8, v143
	s_nop 1
	v_cndmask_b32_e32 v175, v142, v175, vcc
	v_cmp_lt_i32_e32 vcc, 0xd0, v143
	s_nop 1
	v_cndmask_b32_e32 v176, v142, v176, vcc
	v_cmp_lt_i32_e32 vcc, 0xd8, v143
	s_nop 1
	v_cndmask_b32_e32 v177, v142, v177, vcc
	v_cmp_lt_i32_e32 vcc, 0xe0, v143
	s_nop 1
	v_cndmask_b32_e32 v178, v142, v178, vcc
	v_cmp_lt_i32_e32 vcc, 0xe8, v143
	s_nop 1
	v_cndmask_b32_e32 v179, v142, v179, vcc
	v_cmp_lt_i32_e32 vcc, 0xf0, v143
	s_nop 1
	v_cndmask_b32_e32 v180, v142, v180, vcc
	v_cmp_lt_i32_e32 vcc, 0xf8, v143
	s_nop 1
	v_cndmask_b32_e32 v181, v142, v181, vcc
; __device__ __forceinline__ float bf_lo(unsigned v) { return __uint_as_float(v << 16); }
; __device__ __forceinline__ float bf_hi(unsigned v) { return __uint_as_float(v & 0xffff0000u); }
; __device__ __forceinline__ void attn_query8(const unsigned char* __restrict__ KV8, const bf16_t* __restrict__ Z, const int* __restrict__ SEL, bf16_t* __restrict__ YMIX, int t, LAS float* sbuf  ) {
;     ...
;     int iv[4];
; #pragma unroll
;     for (int jj = 0; jj < 4; ++jj) { const int e = lane + 64 * jj; iv[jj] = (e < nsel) ? SEL[(size_t)t * 256 + e] : 0; }
;     f32x2v qf[8];
;     { const u32x4* qp = (const u32x4*)(Z + (size_t)t * ZLD + OFF_Q + lane * 16); const u32x4 a = qp[0], b = qp[1];
;       qf[0] = (f32x2v){bf_lo(a.x), bf_hi(a.x)}; qf[1] = (f32x2v){bf_lo(a.y), bf_hi(a.y)}; qf[2] = (f32x2v){bf_lo(a.z), bf_hi(a.z)}; qf[3] = (f32x2v){bf_lo(a.w), bf_hi(a.w)};
;       qf[4] = (f32x2v){bf_lo(b.x), bf_hi(b.x)}; qf[5] = (f32x2v){bf_lo(b.y), bf_hi(b.y)}; qf[6] = (f32x2v){bf_lo(b.z), bf_hi(b.z)}; qf[7] = (f32x2v){bf_lo(b.w), bf_hi(b.w)}; }
;     ...
;     for (int h = 0; h < 8; ++h) {
;         float sv[4]; float mx = -__builtin_inff();
; #pragma unroll
;         for (int jj = 0; jj < 4; ++jj) { const int j = lane + 64 * jj; const float s = sbuf[h * 256 + j]; sv[jj] = (j < nsel) ? s : -__builtin_inff(); mx = fmaxf(mx, sv[jj]); }
;         mx = wave_max(mx); float sm = 0.f;
; #pragma unroll
;         for (int jj = 0; jj < 4; ++jj) { const int j = lane + 64 * jj; sv[jj] = (j < nsel) ? __expf(sv[jj] - mx) : 0.f; sm += sv[jj]; }
;         sm = wave_sum(sm); const float inv = 1.f / sm;
; #pragma unroll
;         for (int jj = 0; jj < 4; ++jj) sbuf[h * 256 + lane + 64 * jj] = sv[jj] * inv;
;     }
.Latt_nomask:
	s_add_i32 s6, s80, 0x100
	s_min_i32 s6, s6, 0x3fff
	s_min_i32 s8, s6, 0xff
	s_add_i32 s8, s8, 1
	s_lshl_b32 s10, s6, 10
	s_add_u32 s10, s1, s10
	s_addc_u32 s11, s73, 0
	v_mov_b32_e32 v240, 0
	v_add_u32_e32 v133, 0, v144
	v_cmp_gt_i32_e32 vcc, s8, v133
	s_and_saveexec_b64 s[12:13], vcc
	global_load_dword v240, v147, s[10:11] offset:0
	s_mov_b64 exec, s[12:13]
	v_mov_b32_e32 v241, 0
	v_add_u32_e32 v133, 64, v144
	v_cmp_gt_i32_e32 vcc, s8, v133
	s_and_saveexec_b64 s[12:13], vcc
	global_load_dword v241, v147, s[10:11] offset:256
	s_mov_b64 exec, s[12:13]
	v_mov_b32_e32 v242, 0
	v_add_u32_e32 v133, 128, v144
	v_cmp_gt_i32_e32 vcc, s8, v133
	s_and_saveexec_b64 s[12:13], vcc
	global_load_dword v242, v147, s[10:11] offset:512
	s_mov_b64 exec, s[12:13]
	v_mov_b32_e32 v243, 0
	v_add_u32_e32 v133, 192, v144
	v_cmp_gt_i32_e32 vcc, s8, v133
	s_and_saveexec_b64 s[12:13], vcc
	global_load_dword v243, v147, s[10:11] offset:768
	s_mov_b64 exec, s[12:13]
	s_mul_i32 s10, s6, 0x2a00
	s_mul_hi_i32 s11, s6, 0x2a00
	s_add_u32 s10, s42, s10
	s_addc_u32 s11, s43, s11
	global_load_dwordx4 v[244:247], v146, s[10:11] offset:2048
	v_max3_f32 v134, v150, v151, v152
	v_max3_f32 v134, v134, v153, v154
	v_max3_f32 v134, v134, v155, v156
	v_max3_f32 v134, v134, v157, v158
	v_max3_f32 v134, v134, v159, v160
	v_max3_f32 v134, v134, v161, v162
	v_max3_f32 v134, v134, v163, v164
	v_max3_f32 v134, v134, v165, v166
	v_max3_f32 v134, v134, v167, v168
	v_max3_f32 v134, v134, v169, v170
	v_max3_f32 v134, v134, v171, v172
	v_max3_f32 v134, v134, v173, v174
	v_max3_f32 v134, v134, v175, v176
	v_max3_f32 v134, v134, v177, v178
	v_max3_f32 v134, v134, v179, v180
	v_max_f32_e32 v134, v134, v181
	s_nop 1
	v_mov_b32_dpp v135, v134 row_ror:8 row_mask:0xf bank_mask:0xf
	s_nop 0
	v_max_f32_e32 v134, v134, v135
	ds_bpermute_b32 v135, v140, v134
	s_waitcnt lgkmcnt(0)
	v_max_f32_e32 v134, v134, v135
	ds_bpermute_b32 v135, v141, v134
	s_waitcnt lgkmcnt(0)
	v_max_f32_e32 v134, v134, v135
	v_mul_f32_e32 v134, 0xbfb8aa3b, v134
	v_fma_f32 v150, v150, s28, v134
	v_fma_f32 v151, v151, s28, v134
	v_fma_f32 v152, v152, s28, v134
	v_fma_f32 v153, v153, s28, v134
	v_fma_f32 v154, v154, s28, v134
	v_fma_f32 v155, v155, s28, v134
	v_fma_f32 v156, v156, s28, v134
	v_fma_f32 v157, v157, s28, v134
	v_fma_f32 v158, v158, s28, v134
	v_fma_f32 v159, v159, s28, v134
	v_fma_f32 v160, v160, s28, v134
	v_fma_f32 v161, v161, s28, v134
	v_fma_f32 v162, v162, s28, v134
	v_fma_f32 v163, v163, s28, v134
	v_fma_f32 v164, v164, s28, v134
	v_fma_f32 v165, v165, s28, v134
	v_fma_f32 v166, v166, s28, v134
	v_fma_f32 v167, v167, s28, v134
	v_fma_f32 v168, v168, s28, v134
	v_fma_f32 v169, v169, s28, v134
	v_fma_f32 v170, v170, s28, v134
	v_fma_f32 v171, v171, s28, v134
	v_fma_f32 v172, v172, s28, v134
	v_fma_f32 v173, v173, s28, v134
	v_fma_f32 v174, v174, s28, v134
	v_fma_f32 v175, v175, s28, v134
	v_fma_f32 v176, v176, s28, v134
	v_fma_f32 v177, v177, s28, v134
	v_fma_f32 v178, v178, s28, v134
	v_fma_f32 v179, v179, s28, v134
	v_fma_f32 v180, v180, s28, v134
	v_fma_f32 v181, v181, s28, v134
	v_exp_f32_e32 v150, v150
	v_exp_f32_e32 v151, v151
	v_exp_f32_e32 v152, v152
	v_exp_f32_e32 v153, v153
	v_exp_f32_e32 v154, v154
	v_exp_f32_e32 v155, v155
	v_exp_f32_e32 v156, v156
	v_exp_f32_e32 v157, v157
	v_exp_f32_e32 v158, v158
	v_exp_f32_e32 v159, v159
	v_exp_f32_e32 v160, v160
	v_exp_f32_e32 v161, v161
	v_exp_f32_e32 v162, v162
	v_exp_f32_e32 v163, v163
	v_exp_f32_e32 v164, v164
	v_exp_f32_e32 v165, v165
	v_exp_f32_e32 v166, v166
	v_exp_f32_e32 v167, v167
	v_exp_f32_e32 v168, v168
	v_exp_f32_e32 v169, v169
	v_exp_f32_e32 v170, v170
	v_exp_f32_e32 v171, v171
	v_exp_f32_e32 v172, v172
	v_exp_f32_e32 v173, v173
	v_exp_f32_e32 v174, v174
	v_exp_f32_e32 v175, v175
	v_exp_f32_e32 v176, v176
	v_exp_f32_e32 v177, v177
	v_exp_f32_e32 v178, v178
	v_exp_f32_e32 v179, v179
	v_exp_f32_e32 v180, v180
	v_exp_f32_e32 v181, v181
	s_nop 0
	v_add_f32_e32 v134, v150, v151
	v_add_f32_e32 v134, v134, v152
	v_add_f32_e32 v134, v134, v153
	v_add_f32_e32 v134, v134, v154
	v_add_f32_e32 v134, v134, v155
	v_add_f32_e32 v134, v134, v156
	v_add_f32_e32 v134, v134, v157
	v_add_f32_e32 v134, v134, v158
	v_add_f32_e32 v134, v134, v159
	v_add_f32_e32 v134, v134, v160
	v_add_f32_e32 v134, v134, v161
	v_add_f32_e32 v134, v134, v162
	v_add_f32_e32 v134, v134, v163
	v_add_f32_e32 v134, v134, v164
	v_add_f32_e32 v134, v134, v165
	v_add_f32_e32 v134, v134, v166
	v_add_f32_e32 v134, v134, v167
	v_add_f32_e32 v134, v134, v168
	v_add_f32_e32 v134, v134, v169
	v_add_f32_e32 v134, v134, v170
	v_add_f32_e32 v134, v134, v171
	v_add_f32_e32 v134, v134, v172
	v_add_f32_e32 v134, v134, v173
	v_add_f32_e32 v134, v134, v174
	v_add_f32_e32 v134, v134, v175
	v_add_f32_e32 v134, v134, v176
	v_add_f32_e32 v134, v134, v177
	v_add_f32_e32 v134, v134, v178
	v_add_f32_e32 v134, v134, v179
	v_add_f32_e32 v134, v134, v180
	v_add_f32_e32 v134, v134, v181
	s_nop 1
	v_mov_b32_dpp v135, v134 row_ror:8 row_mask:0xf bank_mask:0xf
	s_nop 0
	v_add_f32_e32 v134, v134, v135
	ds_bpermute_b32 v135, v140, v134
	s_waitcnt lgkmcnt(0)
	v_add_f32_e32 v134, v134, v135
	ds_bpermute_b32 v135, v141, v134
	s_waitcnt lgkmcnt(0)
	v_add_f32_e32 v134, v134, v135
	v_div_scale_f32 v132, s[8:9], v134, v134, 1.0
	v_rcp_f32_e32 v135, v132
	v_div_scale_f32 v133, vcc, 1.0, v134, 1.0
	v_fma_f32 v136, -v132, v135, 1.0
	v_fmac_f32_e32 v135, v136, v135
	v_mul_f32_e32 v136, v133, v135
	v_fma_f32 v137, -v132, v136, v133
	v_fmac_f32_e32 v136, v137, v135
	v_fma_f32 v132, -v132, v136, v133
	s_nop 1
	v_div_fmas_f32 v132, v132, v135, v136
	v_div_fixup_f32 v134, v132, v134, 1.0
	v_mov_b32_e32 v149, v134
	v_mov_b32_e32 v198, 0
	v_mov_b32_e32 v199, 0
	v_mov_b32_e32 v200, 0
	v_mov_b32_e32 v201, 0
	v_mov_b32_e32 v202, 0
	v_mov_b32_e32 v203, 0
	v_mov_b32_e32 v204, 0
	v_mov_b32_e32 v205, 0
	v_mov_b32_e32 v206, 0
	v_mov_b32_e32 v207, 0
	v_mov_b32_e32 v208, 0
	v_mov_b32_e32 v209, 0
	v_mov_b32_e32 v210, 0
	v_mov_b32_e32 v211, 0
	v_mov_b32_e32 v212, 0
	v_mov_b32_e32 v213, 0
	s_waitcnt vmcnt(36)
; __device__ __forceinline__ void kv8_pv(const u32x4 (&buf)[8], f32x2v (&o2)[8], const LAS float* srow, int b) {
;     ...
; #pragma unroll
;     for (int u = 0; u < 8; ++u) {
;         const u32x4 v = buf[u]; const f32x2v pp = {p[u], p[u]};
;         o2[0] = __builtin_elementwise_fma(pp, __builtin_amdgcn_cvt_pk_f32_fp8(v.x, false), o2[0]); o2[1] = __builtin_elementwise_fma(pp, __builtin_amdgcn_cvt_pk_f32_fp8(v.x, true), o2[1]);
;         o2[2] = __builtin_elementwise_fma(pp, __builtin_amdgcn_cvt_pk_f32_fp8(v.y, false), o2[2]); o2[3] = __builtin_elementwise_fma(pp, __builtin_amdgcn_cvt_pk_f32_fp8(v.y, true), o2[3]);
;         o2[4] = __builtin_elementwise_fma(pp, __builtin_amdgcn_cvt_pk_f32_fp8(v.z, false), o2[4]); o2[5] = __builtin_elementwise_fma(pp, __builtin_amdgcn_cvt_pk_f32_fp8(v.z, true), o2[5]);
;         o2[6] = __builtin_elementwise_fma(pp, __builtin_amdgcn_cvt_pk_f32_fp8(v.w, false), o2[6]); o2[7] = __builtin_elementwise_fma(pp, __builtin_amdgcn_cvt_pk_f32_fp8(v.w, true), o2[7]);
;     }
	v_cvt_pk_f32_fp8_e32 v[214:215], v0
	v_cvt_pk_f32_fp8_sdwa v[216:217], v0 src0_sel:WORD_1
	v_pk_fma_f32 v[198:199], v[150:151], v[214:215], v[198:199] op_sel_hi:[0,1,1]
	v_pk_fma_f32 v[200:201], v[150:151], v[216:217], v[200:201] op_sel_hi:[0,1,1]
	v_cvt_pk_f32_fp8_e32 v[218:219], v1
	v_cvt_pk_f32_fp8_sdwa v[220:221], v1 src0_sel:WORD_1
	v_pk_fma_f32 v[202:203], v[150:151], v[218:219], v[202:203] op_sel_hi:[0,1,1]
	v_pk_fma_f32 v[204:205], v[150:151], v[220:221], v[204:205] op_sel_hi:[0,1,1]
	v_cvt_pk_f32_fp8_e32 v[214:215], v2
	v_cvt_pk_f32_fp8_sdwa v[216:217], v2 src0_sel:WORD_1
	v_pk_fma_f32 v[206:207], v[150:151], v[214:215], v[206:207] op_sel_hi:[0,1,1]
	v_pk_fma_f32 v[208:209], v[150:151], v[216:217], v[208:209] op_sel_hi:[0,1,1]
	v_cvt_pk_f32_fp8_e32 v[218:219], v3
	v_cvt_pk_f32_fp8_sdwa v[220:221], v3 src0_sel:WORD_1
	v_pk_fma_f32 v[210:211], v[150:151], v[218:219], v[210:211] op_sel_hi:[0,1,1]
	v_pk_fma_f32 v[212:213], v[150:151], v[220:221], v[212:213] op_sel_hi:[0,1,1]
	s_waitcnt vmcnt(35)
	v_cvt_pk_f32_fp8_e32 v[214:215], v4
	v_cvt_pk_f32_fp8_sdwa v[216:217], v4 src0_sel:WORD_1
	v_pk_fma_f32 v[198:199], v[150:151], v[214:215], v[198:199] op_sel:[1,0,0]
	v_pk_fma_f32 v[200:201], v[150:151], v[216:217], v[200:201] op_sel:[1,0,0]
	v_cvt_pk_f32_fp8_e32 v[218:219], v5
	v_cvt_pk_f32_fp8_sdwa v[220:221], v5 src0_sel:WORD_1
	v_pk_fma_f32 v[202:203], v[150:151], v[218:219], v[202:203] op_sel:[1,0,0]
	v_pk_fma_f32 v[204:205], v[150:151], v[220:221], v[204:205] op_sel:[1,0,0]
	v_cvt_pk_f32_fp8_e32 v[214:215], v6
	v_cvt_pk_f32_fp8_sdwa v[216:217], v6 src0_sel:WORD_1
	v_pk_fma_f32 v[206:207], v[150:151], v[214:215], v[206:207] op_sel:[1,0,0]
	v_pk_fma_f32 v[208:209], v[150:151], v[216:217], v[208:209] op_sel:[1,0,0]
	v_cvt_pk_f32_fp8_e32 v[218:219], v7
	v_cvt_pk_f32_fp8_sdwa v[220:221], v7 src0_sel:WORD_1
	v_pk_fma_f32 v[210:211], v[150:151], v[218:219], v[210:211] op_sel:[1,0,0]
	v_pk_fma_f32 v[212:213], v[150:151], v[220:221], v[212:213] op_sel:[1,0,0]
	s_waitcnt vmcnt(34)
	v_cvt_pk_f32_fp8_e32 v[214:215], v8
	v_cvt_pk_f32_fp8_sdwa v[216:217], v8 src0_sel:WORD_1
	v_pk_fma_f32 v[198:199], v[152:153], v[214:215], v[198:199] op_sel_hi:[0,1,1]
	v_pk_fma_f32 v[200:201], v[152:153], v[216:217], v[200:201] op_sel_hi:[0,1,1]
	v_cvt_pk_f32_fp8_e32 v[218:219], v9
	v_cvt_pk_f32_fp8_sdwa v[220:221], v9 src0_sel:WORD_1
	v_pk_fma_f32 v[202:203], v[152:153], v[218:219], v[202:203] op_sel_hi:[0,1,1]
	v_pk_fma_f32 v[204:205], v[152:153], v[220:221], v[204:205] op_sel_hi:[0,1,1]
	v_cvt_pk_f32_fp8_e32 v[214:215], v10
	v_cvt_pk_f32_fp8_sdwa v[216:217], v10 src0_sel:WORD_1
	v_pk_fma_f32 v[206:207], v[152:153], v[214:215], v[206:207] op_sel_hi:[0,1,1]
	v_pk_fma_f32 v[208:209], v[152:153], v[216:217], v[208:209] op_sel_hi:[0,1,1]
	v_cvt_pk_f32_fp8_e32 v[218:219], v11
	v_cvt_pk_f32_fp8_sdwa v[220:221], v11 src0_sel:WORD_1
	v_pk_fma_f32 v[210:211], v[152:153], v[218:219], v[210:211] op_sel_hi:[0,1,1]
	v_pk_fma_f32 v[212:213], v[152:153], v[220:221], v[212:213] op_sel_hi:[0,1,1]
	s_waitcnt vmcnt(33)
	v_cvt_pk_f32_fp8_e32 v[214:215], v12
	v_cvt_pk_f32_fp8_sdwa v[216:217], v12 src0_sel:WORD_1
	v_pk_fma_f32 v[198:199], v[152:153], v[214:215], v[198:199] op_sel:[1,0,0]
	v_pk_fma_f32 v[200:201], v[152:153], v[216:217], v[200:201] op_sel:[1,0,0]
	v_cvt_pk_f32_fp8_e32 v[218:219], v13
	v_cvt_pk_f32_fp8_sdwa v[220:221], v13 src0_sel:WORD_1
	v_pk_fma_f32 v[202:203], v[152:153], v[218:219], v[202:203] op_sel:[1,0,0]
	v_pk_fma_f32 v[204:205], v[152:153], v[220:221], v[204:205] op_sel:[1,0,0]
	v_cvt_pk_f32_fp8_e32 v[214:215], v14
	v_cvt_pk_f32_fp8_sdwa v[216:217], v14 src0_sel:WORD_1
	v_pk_fma_f32 v[206:207], v[152:153], v[214:215], v[206:207] op_sel:[1,0,0]
	v_pk_fma_f32 v[208:209], v[152:153], v[216:217], v[208:209] op_sel:[1,0,0]
	v_cvt_pk_f32_fp8_e32 v[218:219], v15
	v_cvt_pk_f32_fp8_sdwa v[220:221], v15 src0_sel:WORD_1
	v_pk_fma_f32 v[210:211], v[152:153], v[218:219], v[210:211] op_sel:[1,0,0]
	v_pk_fma_f32 v[212:213], v[152:153], v[220:221], v[212:213] op_sel:[1,0,0]
	s_waitcnt vmcnt(32)
	v_cvt_pk_f32_fp8_e32 v[214:215], v16
	v_cvt_pk_f32_fp8_sdwa v[216:217], v16 src0_sel:WORD_1
	v_pk_fma_f32 v[198:199], v[154:155], v[214:215], v[198:199] op_sel_hi:[0,1,1]
	v_pk_fma_f32 v[200:201], v[154:155], v[216:217], v[200:201] op_sel_hi:[0,1,1]
	v_cvt_pk_f32_fp8_e32 v[218:219], v17
	v_cvt_pk_f32_fp8_sdwa v[220:221], v17 src0_sel:WORD_1
	v_pk_fma_f32 v[202:203], v[154:155], v[218:219], v[202:203] op_sel_hi:[0,1,1]
	v_pk_fma_f32 v[204:205], v[154:155], v[220:221], v[204:205] op_sel_hi:[0,1,1]
	v_cvt_pk_f32_fp8_e32 v[214:215], v18
	v_cvt_pk_f32_fp8_sdwa v[216:217], v18 src0_sel:WORD_1
	v_pk_fma_f32 v[206:207], v[154:155], v[214:215], v[206:207] op_sel_hi:[0,1,1]
	v_pk_fma_f32 v[208:209], v[154:155], v[216:217], v[208:209] op_sel_hi:[0,1,1]
	v_cvt_pk_f32_fp8_e32 v[218:219], v19
	v_cvt_pk_f32_fp8_sdwa v[220:221], v19 src0_sel:WORD_1
	v_pk_fma_f32 v[210:211], v[154:155], v[218:219], v[210:211] op_sel_hi:[0,1,1]
	v_pk_fma_f32 v[212:213], v[154:155], v[220:221], v[212:213] op_sel_hi:[0,1,1]
	s_waitcnt vmcnt(31)
	v_cvt_pk_f32_fp8_e32 v[214:215], v20
	v_cvt_pk_f32_fp8_sdwa v[216:217], v20 src0_sel:WORD_1
	v_pk_fma_f32 v[198:199], v[154:155], v[214:215], v[198:199] op_sel:[1,0,0]
	v_pk_fma_f32 v[200:201], v[154:155], v[216:217], v[200:201] op_sel:[1,0,0]
	v_cvt_pk_f32_fp8_e32 v[218:219], v21
	v_cvt_pk_f32_fp8_sdwa v[220:221], v21 src0_sel:WORD_1
	v_pk_fma_f32 v[202:203], v[154:155], v[218:219], v[202:203] op_sel:[1,0,0]
	v_pk_fma_f32 v[204:205], v[154:155], v[220:221], v[204:205] op_sel:[1,0,0]
	v_cvt_pk_f32_fp8_e32 v[214:215], v22
	v_cvt_pk_f32_fp8_sdwa v[216:217], v22 src0_sel:WORD_1
	v_pk_fma_f32 v[206:207], v[154:155], v[214:215], v[206:207] op_sel:[1,0,0]
	v_pk_fma_f32 v[208:209], v[154:155], v[216:217], v[208:209] op_sel:[1,0,0]
	v_cvt_pk_f32_fp8_e32 v[218:219], v23
	v_cvt_pk_f32_fp8_sdwa v[220:221], v23 src0_sel:WORD_1
	v_pk_fma_f32 v[210:211], v[154:155], v[218:219], v[210:211] op_sel:[1,0,0]
	v_pk_fma_f32 v[212:213], v[154:155], v[220:221], v[212:213] op_sel:[1,0,0]
	s_waitcnt vmcnt(30)
; __device__ __forceinline__ void kv8_pv(const u32x4 (&buf)[8], f32x2v (&o2)[8], const LAS float* srow, int b) {
;     ...
; #pragma unroll
;     for (int u = 0; u < 8; ++u) {
;         const u32x4 v = buf[u]; const f32x2v pp = {p[u], p[u]};
;         o2[0] = __builtin_elementwise_fma(pp, __builtin_amdgcn_cvt_pk_f32_fp8(v.x, false), o2[0]); o2[1] = __builtin_elementwise_fma(pp, __builtin_amdgcn_cvt_pk_f32_fp8(v.x, true), o2[1]);
;         o2[2] = __builtin_elementwise_fma(pp, __builtin_amdgcn_cvt_pk_f32_fp8(v.y, false), o2[2]); o2[3] = __builtin_elementwise_fma(pp, __builtin_amdgcn_cvt_pk_f32_fp8(v.y, true), o2[3]);
;         o2[4] = __builtin_elementwise_fma(pp, __builtin_amdgcn_cvt_pk_f32_fp8(v.z, false), o2[4]); o2[5] = __builtin_elementwise_fma(pp, __builtin_amdgcn_cvt_pk_f32_fp8(v.z, true), o2[5]);
;         o2[6] = __builtin_elementwise_fma(pp, __builtin_amdgcn_cvt_pk_f32_fp8(v.w, false), o2[6]); o2[7] = __builtin_elementwise_fma(pp, __builtin_amdgcn_cvt_pk_f32_fp8(v.w, true), o2[7]);
;     }
	v_cvt_pk_f32_fp8_e32 v[214:215], v24
	v_cvt_pk_f32_fp8_sdwa v[216:217], v24 src0_sel:WORD_1
	v_pk_fma_f32 v[198:199], v[156:157], v[214:215], v[198:199] op_sel_hi:[0,1,1]
	v_pk_fma_f32 v[200:201], v[156:157], v[216:217], v[200:201] op_sel_hi:[0,1,1]
	v_cvt_pk_f32_fp8_e32 v[218:219], v25
	v_cvt_pk_f32_fp8_sdwa v[220:221], v25 src0_sel:WORD_1
	v_pk_fma_f32 v[202:203], v[156:157], v[218:219], v[202:203] op_sel_hi:[0,1,1]
	v_pk_fma_f32 v[204:205], v[156:157], v[220:221], v[204:205] op_sel_hi:[0,1,1]
	v_cvt_pk_f32_fp8_e32 v[214:215], v26
	v_cvt_pk_f32_fp8_sdwa v[216:217], v26 src0_sel:WORD_1
	v_pk_fma_f32 v[206:207], v[156:157], v[214:215], v[206:207] op_sel_hi:[0,1,1]
	v_pk_fma_f32 v[208:209], v[156:157], v[216:217], v[208:209] op_sel_hi:[0,1,1]
	v_cvt_pk_f32_fp8_e32 v[218:219], v27
	v_cvt_pk_f32_fp8_sdwa v[220:221], v27 src0_sel:WORD_1
	v_pk_fma_f32 v[210:211], v[156:157], v[218:219], v[210:211] op_sel_hi:[0,1,1]
	v_pk_fma_f32 v[212:213], v[156:157], v[220:221], v[212:213] op_sel_hi:[0,1,1]
	s_waitcnt vmcnt(29)
	v_cvt_pk_f32_fp8_e32 v[214:215], v28
	v_cvt_pk_f32_fp8_sdwa v[216:217], v28 src0_sel:WORD_1
	v_pk_fma_f32 v[198:199], v[156:157], v[214:215], v[198:199] op_sel:[1,0,0]
	v_pk_fma_f32 v[200:201], v[156:157], v[216:217], v[200:201] op_sel:[1,0,0]
	v_cvt_pk_f32_fp8_e32 v[218:219], v29
	v_cvt_pk_f32_fp8_sdwa v[220:221], v29 src0_sel:WORD_1
	v_pk_fma_f32 v[202:203], v[156:157], v[218:219], v[202:203] op_sel:[1,0,0]
	v_pk_fma_f32 v[204:205], v[156:157], v[220:221], v[204:205] op_sel:[1,0,0]
	v_cvt_pk_f32_fp8_e32 v[214:215], v30
	v_cvt_pk_f32_fp8_sdwa v[216:217], v30 src0_sel:WORD_1
	v_pk_fma_f32 v[206:207], v[156:157], v[214:215], v[206:207] op_sel:[1,0,0]
	v_pk_fma_f32 v[208:209], v[156:157], v[216:217], v[208:209] op_sel:[1,0,0]
	v_cvt_pk_f32_fp8_e32 v[218:219], v31
	v_cvt_pk_f32_fp8_sdwa v[220:221], v31 src0_sel:WORD_1
	v_pk_fma_f32 v[210:211], v[156:157], v[218:219], v[210:211] op_sel:[1,0,0]
	v_pk_fma_f32 v[212:213], v[156:157], v[220:221], v[212:213] op_sel:[1,0,0]
	s_waitcnt vmcnt(28)
	v_cvt_pk_f32_fp8_e32 v[214:215], v32
	v_cvt_pk_f32_fp8_sdwa v[216:217], v32 src0_sel:WORD_1
	v_pk_fma_f32 v[198:199], v[158:159], v[214:215], v[198:199] op_sel_hi:[0,1,1]
	v_pk_fma_f32 v[200:201], v[158:159], v[216:217], v[200:201] op_sel_hi:[0,1,1]
	v_cvt_pk_f32_fp8_e32 v[218:219], v33
	v_cvt_pk_f32_fp8_sdwa v[220:221], v33 src0_sel:WORD_1
	v_pk_fma_f32 v[202:203], v[158:159], v[218:219], v[202:203] op_sel_hi:[0,1,1]
	v_pk_fma_f32 v[204:205], v[158:159], v[220:221], v[204:205] op_sel_hi:[0,1,1]
	v_cvt_pk_f32_fp8_e32 v[214:215], v34
	v_cvt_pk_f32_fp8_sdwa v[216:217], v34 src0_sel:WORD_1
	v_pk_fma_f32 v[206:207], v[158:159], v[214:215], v[206:207] op_sel_hi:[0,1,1]
	v_pk_fma_f32 v[208:209], v[158:159], v[216:217], v[208:209] op_sel_hi:[0,1,1]
	v_cvt_pk_f32_fp8_e32 v[218:219], v35
	v_cvt_pk_f32_fp8_sdwa v[220:221], v35 src0_sel:WORD_1
	v_pk_fma_f32 v[210:211], v[158:159], v[218:219], v[210:211] op_sel_hi:[0,1,1]
	v_pk_fma_f32 v[212:213], v[158:159], v[220:221], v[212:213] op_sel_hi:[0,1,1]
	s_waitcnt vmcnt(27)
	v_cvt_pk_f32_fp8_e32 v[214:215], v36
	v_cvt_pk_f32_fp8_sdwa v[216:217], v36 src0_sel:WORD_1
	v_pk_fma_f32 v[198:199], v[158:159], v[214:215], v[198:199] op_sel:[1,0,0]
	v_pk_fma_f32 v[200:201], v[158:159], v[216:217], v[200:201] op_sel:[1,0,0]
	v_cvt_pk_f32_fp8_e32 v[218:219], v37
	v_cvt_pk_f32_fp8_sdwa v[220:221], v37 src0_sel:WORD_1
	v_pk_fma_f32 v[202:203], v[158:159], v[218:219], v[202:203] op_sel:[1,0,0]
	v_pk_fma_f32 v[204:205], v[158:159], v[220:221], v[204:205] op_sel:[1,0,0]
	v_cvt_pk_f32_fp8_e32 v[214:215], v38
	v_cvt_pk_f32_fp8_sdwa v[216:217], v38 src0_sel:WORD_1
	v_pk_fma_f32 v[206:207], v[158:159], v[214:215], v[206:207] op_sel:[1,0,0]
	v_pk_fma_f32 v[208:209], v[158:159], v[216:217], v[208:209] op_sel:[1,0,0]
	v_cvt_pk_f32_fp8_e32 v[218:219], v39
	v_cvt_pk_f32_fp8_sdwa v[220:221], v39 src0_sel:WORD_1
	v_pk_fma_f32 v[210:211], v[158:159], v[218:219], v[210:211] op_sel:[1,0,0]
	v_pk_fma_f32 v[212:213], v[158:159], v[220:221], v[212:213] op_sel:[1,0,0]
	s_waitcnt vmcnt(26)
	v_cvt_pk_f32_fp8_e32 v[214:215], v40
	v_cvt_pk_f32_fp8_sdwa v[216:217], v40 src0_sel:WORD_1
	v_pk_fma_f32 v[198:199], v[160:161], v[214:215], v[198:199] op_sel_hi:[0,1,1]
	v_pk_fma_f32 v[200:201], v[160:161], v[216:217], v[200:201] op_sel_hi:[0,1,1]
	v_cvt_pk_f32_fp8_e32 v[218:219], v41
	v_cvt_pk_f32_fp8_sdwa v[220:221], v41 src0_sel:WORD_1
	v_pk_fma_f32 v[202:203], v[160:161], v[218:219], v[202:203] op_sel_hi:[0,1,1]
	v_pk_fma_f32 v[204:205], v[160:161], v[220:221], v[204:205] op_sel_hi:[0,1,1]
	v_cvt_pk_f32_fp8_e32 v[214:215], v42
	v_cvt_pk_f32_fp8_sdwa v[216:217], v42 src0_sel:WORD_1
	v_pk_fma_f32 v[206:207], v[160:161], v[214:215], v[206:207] op_sel_hi:[0,1,1]
	v_pk_fma_f32 v[208:209], v[160:161], v[216:217], v[208:209] op_sel_hi:[0,1,1]
	v_cvt_pk_f32_fp8_e32 v[218:219], v43
	v_cvt_pk_f32_fp8_sdwa v[220:221], v43 src0_sel:WORD_1
	v_pk_fma_f32 v[210:211], v[160:161], v[218:219], v[210:211] op_sel_hi:[0,1,1]
	v_pk_fma_f32 v[212:213], v[160:161], v[220:221], v[212:213] op_sel_hi:[0,1,1]
	s_waitcnt vmcnt(25)
	v_cvt_pk_f32_fp8_e32 v[214:215], v44
	v_cvt_pk_f32_fp8_sdwa v[216:217], v44 src0_sel:WORD_1
	v_pk_fma_f32 v[198:199], v[160:161], v[214:215], v[198:199] op_sel:[1,0,0]
	v_pk_fma_f32 v[200:201], v[160:161], v[216:217], v[200:201] op_sel:[1,0,0]
	v_cvt_pk_f32_fp8_e32 v[218:219], v45
	v_cvt_pk_f32_fp8_sdwa v[220:221], v45 src0_sel:WORD_1
	v_pk_fma_f32 v[202:203], v[160:161], v[218:219], v[202:203] op_sel:[1,0,0]
	v_pk_fma_f32 v[204:205], v[160:161], v[220:221], v[204:205] op_sel:[1,0,0]
	v_cvt_pk_f32_fp8_e32 v[214:215], v46
	v_cvt_pk_f32_fp8_sdwa v[216:217], v46 src0_sel:WORD_1
	v_pk_fma_f32 v[206:207], v[160:161], v[214:215], v[206:207] op_sel:[1,0,0]
	v_pk_fma_f32 v[208:209], v[160:161], v[216:217], v[208:209] op_sel:[1,0,0]
	v_cvt_pk_f32_fp8_e32 v[218:219], v47
	v_cvt_pk_f32_fp8_sdwa v[220:221], v47 src0_sel:WORD_1
	v_pk_fma_f32 v[210:211], v[160:161], v[218:219], v[210:211] op_sel:[1,0,0]
	v_pk_fma_f32 v[212:213], v[160:161], v[220:221], v[212:213] op_sel:[1,0,0]
	s_waitcnt vmcnt(24)
; __device__ __forceinline__ void kv8_pv(const u32x4 (&buf)[8], f32x2v (&o2)[8], const LAS float* srow, int b) {
;     ...
; #pragma unroll
;     for (int u = 0; u < 8; ++u) {
;         const u32x4 v = buf[u]; const f32x2v pp = {p[u], p[u]};
;         o2[0] = __builtin_elementwise_fma(pp, __builtin_amdgcn_cvt_pk_f32_fp8(v.x, false), o2[0]); o2[1] = __builtin_elementwise_fma(pp, __builtin_amdgcn_cvt_pk_f32_fp8(v.x, true), o2[1]);
;         o2[2] = __builtin_elementwise_fma(pp, __builtin_amdgcn_cvt_pk_f32_fp8(v.y, false), o2[2]); o2[3] = __builtin_elementwise_fma(pp, __builtin_amdgcn_cvt_pk_f32_fp8(v.y, true), o2[3]);
;         o2[4] = __builtin_elementwise_fma(pp, __builtin_amdgcn_cvt_pk_f32_fp8(v.z, false), o2[4]); o2[5] = __builtin_elementwise_fma(pp, __builtin_amdgcn_cvt_pk_f32_fp8(v.z, true), o2[5]);
;         o2[6] = __builtin_elementwise_fma(pp, __builtin_amdgcn_cvt_pk_f32_fp8(v.w, false), o2[6]); o2[7] = __builtin_elementwise_fma(pp, __builtin_amdgcn_cvt_pk_f32_fp8(v.w, true), o2[7]);
;     }
	v_cvt_pk_f32_fp8_e32 v[214:215], v48
	v_cvt_pk_f32_fp8_sdwa v[216:217], v48 src0_sel:WORD_1
	v_pk_fma_f32 v[198:199], v[162:163], v[214:215], v[198:199] op_sel_hi:[0,1,1]
	v_pk_fma_f32 v[200:201], v[162:163], v[216:217], v[200:201] op_sel_hi:[0,1,1]
	v_cvt_pk_f32_fp8_e32 v[218:219], v49
	v_cvt_pk_f32_fp8_sdwa v[220:221], v49 src0_sel:WORD_1
	v_pk_fma_f32 v[202:203], v[162:163], v[218:219], v[202:203] op_sel_hi:[0,1,1]
	v_pk_fma_f32 v[204:205], v[162:163], v[220:221], v[204:205] op_sel_hi:[0,1,1]
	v_cvt_pk_f32_fp8_e32 v[214:215], v50
	v_cvt_pk_f32_fp8_sdwa v[216:217], v50 src0_sel:WORD_1
	v_pk_fma_f32 v[206:207], v[162:163], v[214:215], v[206:207] op_sel_hi:[0,1,1]
	v_pk_fma_f32 v[208:209], v[162:163], v[216:217], v[208:209] op_sel_hi:[0,1,1]
	v_cvt_pk_f32_fp8_e32 v[218:219], v51
	v_cvt_pk_f32_fp8_sdwa v[220:221], v51 src0_sel:WORD_1
	v_pk_fma_f32 v[210:211], v[162:163], v[218:219], v[210:211] op_sel_hi:[0,1,1]
	v_pk_fma_f32 v[212:213], v[162:163], v[220:221], v[212:213] op_sel_hi:[0,1,1]
	s_waitcnt vmcnt(23)
	v_cvt_pk_f32_fp8_e32 v[214:215], v52
	v_cvt_pk_f32_fp8_sdwa v[216:217], v52 src0_sel:WORD_1
	v_pk_fma_f32 v[198:199], v[162:163], v[214:215], v[198:199] op_sel:[1,0,0]
	v_pk_fma_f32 v[200:201], v[162:163], v[216:217], v[200:201] op_sel:[1,0,0]
	v_cvt_pk_f32_fp8_e32 v[218:219], v53
	v_cvt_pk_f32_fp8_sdwa v[220:221], v53 src0_sel:WORD_1
	v_pk_fma_f32 v[202:203], v[162:163], v[218:219], v[202:203] op_sel:[1,0,0]
	v_pk_fma_f32 v[204:205], v[162:163], v[220:221], v[204:205] op_sel:[1,0,0]
	v_cvt_pk_f32_fp8_e32 v[214:215], v54
	v_cvt_pk_f32_fp8_sdwa v[216:217], v54 src0_sel:WORD_1
	v_pk_fma_f32 v[206:207], v[162:163], v[214:215], v[206:207] op_sel:[1,0,0]
	v_pk_fma_f32 v[208:209], v[162:163], v[216:217], v[208:209] op_sel:[1,0,0]
	v_cvt_pk_f32_fp8_e32 v[218:219], v55
	v_cvt_pk_f32_fp8_sdwa v[220:221], v55 src0_sel:WORD_1
	v_pk_fma_f32 v[210:211], v[162:163], v[218:219], v[210:211] op_sel:[1,0,0]
	v_pk_fma_f32 v[212:213], v[162:163], v[220:221], v[212:213] op_sel:[1,0,0]
	s_waitcnt vmcnt(22)
	v_cvt_pk_f32_fp8_e32 v[214:215], v56
	v_cvt_pk_f32_fp8_sdwa v[216:217], v56 src0_sel:WORD_1
	v_pk_fma_f32 v[198:199], v[164:165], v[214:215], v[198:199] op_sel_hi:[0,1,1]
	v_pk_fma_f32 v[200:201], v[164:165], v[216:217], v[200:201] op_sel_hi:[0,1,1]
	v_cvt_pk_f32_fp8_e32 v[218:219], v57
	v_cvt_pk_f32_fp8_sdwa v[220:221], v57 src0_sel:WORD_1
	v_pk_fma_f32 v[202:203], v[164:165], v[218:219], v[202:203] op_sel_hi:[0,1,1]
	v_pk_fma_f32 v[204:205], v[164:165], v[220:221], v[204:205] op_sel_hi:[0,1,1]
	v_cvt_pk_f32_fp8_e32 v[214:215], v58
	v_cvt_pk_f32_fp8_sdwa v[216:217], v58 src0_sel:WORD_1
	v_pk_fma_f32 v[206:207], v[164:165], v[214:215], v[206:207] op_sel_hi:[0,1,1]
	v_pk_fma_f32 v[208:209], v[164:165], v[216:217], v[208:209] op_sel_hi:[0,1,1]
	v_cvt_pk_f32_fp8_e32 v[218:219], v59
	v_cvt_pk_f32_fp8_sdwa v[220:221], v59 src0_sel:WORD_1
	v_pk_fma_f32 v[210:211], v[164:165], v[218:219], v[210:211] op_sel_hi:[0,1,1]
	v_pk_fma_f32 v[212:213], v[164:165], v[220:221], v[212:213] op_sel_hi:[0,1,1]
	s_waitcnt vmcnt(21)
	v_cvt_pk_f32_fp8_e32 v[214:215], v60
	v_cvt_pk_f32_fp8_sdwa v[216:217], v60 src0_sel:WORD_1
	v_pk_fma_f32 v[198:199], v[164:165], v[214:215], v[198:199] op_sel:[1,0,0]
	v_pk_fma_f32 v[200:201], v[164:165], v[216:217], v[200:201] op_sel:[1,0,0]
	v_cvt_pk_f32_fp8_e32 v[218:219], v61
	v_cvt_pk_f32_fp8_sdwa v[220:221], v61 src0_sel:WORD_1
	v_pk_fma_f32 v[202:203], v[164:165], v[218:219], v[202:203] op_sel:[1,0,0]
	v_pk_fma_f32 v[204:205], v[164:165], v[220:221], v[204:205] op_sel:[1,0,0]
	v_cvt_pk_f32_fp8_e32 v[214:215], v62
	v_cvt_pk_f32_fp8_sdwa v[216:217], v62 src0_sel:WORD_1
	v_pk_fma_f32 v[206:207], v[164:165], v[214:215], v[206:207] op_sel:[1,0,0]
	v_pk_fma_f32 v[208:209], v[164:165], v[216:217], v[208:209] op_sel:[1,0,0]
	v_cvt_pk_f32_fp8_e32 v[218:219], v63
	v_cvt_pk_f32_fp8_sdwa v[220:221], v63 src0_sel:WORD_1
	v_pk_fma_f32 v[210:211], v[164:165], v[218:219], v[210:211] op_sel:[1,0,0]
	v_pk_fma_f32 v[212:213], v[164:165], v[220:221], v[212:213] op_sel:[1,0,0]
	s_waitcnt vmcnt(20)
	v_cvt_pk_f32_fp8_e32 v[214:215], v64
	v_cvt_pk_f32_fp8_sdwa v[216:217], v64 src0_sel:WORD_1
	v_pk_fma_f32 v[198:199], v[166:167], v[214:215], v[198:199] op_sel_hi:[0,1,1]
	v_pk_fma_f32 v[200:201], v[166:167], v[216:217], v[200:201] op_sel_hi:[0,1,1]
	v_cvt_pk_f32_fp8_e32 v[218:219], v65
	v_cvt_pk_f32_fp8_sdwa v[220:221], v65 src0_sel:WORD_1
	v_pk_fma_f32 v[202:203], v[166:167], v[218:219], v[202:203] op_sel_hi:[0,1,1]
	v_pk_fma_f32 v[204:205], v[166:167], v[220:221], v[204:205] op_sel_hi:[0,1,1]
	v_cvt_pk_f32_fp8_e32 v[214:215], v66
	v_cvt_pk_f32_fp8_sdwa v[216:217], v66 src0_sel:WORD_1
	v_pk_fma_f32 v[206:207], v[166:167], v[214:215], v[206:207] op_sel_hi:[0,1,1]
	v_pk_fma_f32 v[208:209], v[166:167], v[216:217], v[208:209] op_sel_hi:[0,1,1]
	v_cvt_pk_f32_fp8_e32 v[218:219], v67
	v_cvt_pk_f32_fp8_sdwa v[220:221], v67 src0_sel:WORD_1
	v_pk_fma_f32 v[210:211], v[166:167], v[218:219], v[210:211] op_sel_hi:[0,1,1]
	v_pk_fma_f32 v[212:213], v[166:167], v[220:221], v[212:213] op_sel_hi:[0,1,1]
	s_waitcnt vmcnt(19)
	v_cvt_pk_f32_fp8_e32 v[214:215], v68
	v_cvt_pk_f32_fp8_sdwa v[216:217], v68 src0_sel:WORD_1
	v_pk_fma_f32 v[198:199], v[166:167], v[214:215], v[198:199] op_sel:[1,0,0]
	v_pk_fma_f32 v[200:201], v[166:167], v[216:217], v[200:201] op_sel:[1,0,0]
	v_cvt_pk_f32_fp8_e32 v[218:219], v69
	v_cvt_pk_f32_fp8_sdwa v[220:221], v69 src0_sel:WORD_1
	v_pk_fma_f32 v[202:203], v[166:167], v[218:219], v[202:203] op_sel:[1,0,0]
	v_pk_fma_f32 v[204:205], v[166:167], v[220:221], v[204:205] op_sel:[1,0,0]
	v_cvt_pk_f32_fp8_e32 v[214:215], v70
	v_cvt_pk_f32_fp8_sdwa v[216:217], v70 src0_sel:WORD_1
	v_pk_fma_f32 v[206:207], v[166:167], v[214:215], v[206:207] op_sel:[1,0,0]
	v_pk_fma_f32 v[208:209], v[166:167], v[216:217], v[208:209] op_sel:[1,0,0]
	v_cvt_pk_f32_fp8_e32 v[218:219], v71
	v_cvt_pk_f32_fp8_sdwa v[220:221], v71 src0_sel:WORD_1
	v_pk_fma_f32 v[210:211], v[166:167], v[218:219], v[210:211] op_sel:[1,0,0]
	v_pk_fma_f32 v[212:213], v[166:167], v[220:221], v[212:213] op_sel:[1,0,0]
	s_waitcnt vmcnt(18)
; __device__ __forceinline__ void kv8_pv(const u32x4 (&buf)[8], f32x2v (&o2)[8], const LAS float* srow, int b) {
;     ...
; #pragma unroll
;     for (int u = 0; u < 8; ++u) {
;         const u32x4 v = buf[u]; const f32x2v pp = {p[u], p[u]};
;         o2[0] = __builtin_elementwise_fma(pp, __builtin_amdgcn_cvt_pk_f32_fp8(v.x, false), o2[0]); o2[1] = __builtin_elementwise_fma(pp, __builtin_amdgcn_cvt_pk_f32_fp8(v.x, true), o2[1]);
;         o2[2] = __builtin_elementwise_fma(pp, __builtin_amdgcn_cvt_pk_f32_fp8(v.y, false), o2[2]); o2[3] = __builtin_elementwise_fma(pp, __builtin_amdgcn_cvt_pk_f32_fp8(v.y, true), o2[3]);
;         o2[4] = __builtin_elementwise_fma(pp, __builtin_amdgcn_cvt_pk_f32_fp8(v.z, false), o2[4]); o2[5] = __builtin_elementwise_fma(pp, __builtin_amdgcn_cvt_pk_f32_fp8(v.z, true), o2[5]);
;         o2[6] = __builtin_elementwise_fma(pp, __builtin_amdgcn_cvt_pk_f32_fp8(v.w, false), o2[6]); o2[7] = __builtin_elementwise_fma(pp, __builtin_amdgcn_cvt_pk_f32_fp8(v.w, true), o2[7]);
;     }
	v_cvt_pk_f32_fp8_e32 v[214:215], v72
	v_cvt_pk_f32_fp8_sdwa v[216:217], v72 src0_sel:WORD_1
	v_pk_fma_f32 v[198:199], v[168:169], v[214:215], v[198:199] op_sel_hi:[0,1,1]
	v_pk_fma_f32 v[200:201], v[168:169], v[216:217], v[200:201] op_sel_hi:[0,1,1]
	v_cvt_pk_f32_fp8_e32 v[218:219], v73
	v_cvt_pk_f32_fp8_sdwa v[220:221], v73 src0_sel:WORD_1
	v_pk_fma_f32 v[202:203], v[168:169], v[218:219], v[202:203] op_sel_hi:[0,1,1]
	v_pk_fma_f32 v[204:205], v[168:169], v[220:221], v[204:205] op_sel_hi:[0,1,1]
	v_cvt_pk_f32_fp8_e32 v[214:215], v74
	v_cvt_pk_f32_fp8_sdwa v[216:217], v74 src0_sel:WORD_1
	v_pk_fma_f32 v[206:207], v[168:169], v[214:215], v[206:207] op_sel_hi:[0,1,1]
	v_pk_fma_f32 v[208:209], v[168:169], v[216:217], v[208:209] op_sel_hi:[0,1,1]
	v_cvt_pk_f32_fp8_e32 v[218:219], v75
	v_cvt_pk_f32_fp8_sdwa v[220:221], v75 src0_sel:WORD_1
	v_pk_fma_f32 v[210:211], v[168:169], v[218:219], v[210:211] op_sel_hi:[0,1,1]
	v_pk_fma_f32 v[212:213], v[168:169], v[220:221], v[212:213] op_sel_hi:[0,1,1]
	s_waitcnt vmcnt(17)
	v_cvt_pk_f32_fp8_e32 v[214:215], v76
	v_cvt_pk_f32_fp8_sdwa v[216:217], v76 src0_sel:WORD_1
	v_pk_fma_f32 v[198:199], v[168:169], v[214:215], v[198:199] op_sel:[1,0,0]
	v_pk_fma_f32 v[200:201], v[168:169], v[216:217], v[200:201] op_sel:[1,0,0]
	v_cvt_pk_f32_fp8_e32 v[218:219], v77
	v_cvt_pk_f32_fp8_sdwa v[220:221], v77 src0_sel:WORD_1
	v_pk_fma_f32 v[202:203], v[168:169], v[218:219], v[202:203] op_sel:[1,0,0]
	v_pk_fma_f32 v[204:205], v[168:169], v[220:221], v[204:205] op_sel:[1,0,0]
	v_cvt_pk_f32_fp8_e32 v[214:215], v78
	v_cvt_pk_f32_fp8_sdwa v[216:217], v78 src0_sel:WORD_1
	v_pk_fma_f32 v[206:207], v[168:169], v[214:215], v[206:207] op_sel:[1,0,0]
	v_pk_fma_f32 v[208:209], v[168:169], v[216:217], v[208:209] op_sel:[1,0,0]
	v_cvt_pk_f32_fp8_e32 v[218:219], v79
	v_cvt_pk_f32_fp8_sdwa v[220:221], v79 src0_sel:WORD_1
	v_pk_fma_f32 v[210:211], v[168:169], v[218:219], v[210:211] op_sel:[1,0,0]
	v_pk_fma_f32 v[212:213], v[168:169], v[220:221], v[212:213] op_sel:[1,0,0]
	s_waitcnt vmcnt(16)
	v_cvt_pk_f32_fp8_e32 v[214:215], v80
	v_cvt_pk_f32_fp8_sdwa v[216:217], v80 src0_sel:WORD_1
	v_pk_fma_f32 v[198:199], v[170:171], v[214:215], v[198:199] op_sel_hi:[0,1,1]
	v_pk_fma_f32 v[200:201], v[170:171], v[216:217], v[200:201] op_sel_hi:[0,1,1]
	v_cvt_pk_f32_fp8_e32 v[218:219], v81
	v_cvt_pk_f32_fp8_sdwa v[220:221], v81 src0_sel:WORD_1
	v_pk_fma_f32 v[202:203], v[170:171], v[218:219], v[202:203] op_sel_hi:[0,1,1]
	v_pk_fma_f32 v[204:205], v[170:171], v[220:221], v[204:205] op_sel_hi:[0,1,1]
	v_cvt_pk_f32_fp8_e32 v[214:215], v82
	v_cvt_pk_f32_fp8_sdwa v[216:217], v82 src0_sel:WORD_1
	v_pk_fma_f32 v[206:207], v[170:171], v[214:215], v[206:207] op_sel_hi:[0,1,1]
	v_pk_fma_f32 v[208:209], v[170:171], v[216:217], v[208:209] op_sel_hi:[0,1,1]
	v_cvt_pk_f32_fp8_e32 v[218:219], v83
	v_cvt_pk_f32_fp8_sdwa v[220:221], v83 src0_sel:WORD_1
	v_pk_fma_f32 v[210:211], v[170:171], v[218:219], v[210:211] op_sel_hi:[0,1,1]
	v_pk_fma_f32 v[212:213], v[170:171], v[220:221], v[212:213] op_sel_hi:[0,1,1]
	s_waitcnt vmcnt(15)
	v_cvt_pk_f32_fp8_e32 v[214:215], v84
	v_cvt_pk_f32_fp8_sdwa v[216:217], v84 src0_sel:WORD_1
	v_pk_fma_f32 v[198:199], v[170:171], v[214:215], v[198:199] op_sel:[1,0,0]
	v_pk_fma_f32 v[200:201], v[170:171], v[216:217], v[200:201] op_sel:[1,0,0]
	v_cvt_pk_f32_fp8_e32 v[218:219], v85
	v_cvt_pk_f32_fp8_sdwa v[220:221], v85 src0_sel:WORD_1
	v_pk_fma_f32 v[202:203], v[170:171], v[218:219], v[202:203] op_sel:[1,0,0]
	v_pk_fma_f32 v[204:205], v[170:171], v[220:221], v[204:205] op_sel:[1,0,0]
	v_cvt_pk_f32_fp8_e32 v[214:215], v86
	v_cvt_pk_f32_fp8_sdwa v[216:217], v86 src0_sel:WORD_1
	v_pk_fma_f32 v[206:207], v[170:171], v[214:215], v[206:207] op_sel:[1,0,0]
	v_pk_fma_f32 v[208:209], v[170:171], v[216:217], v[208:209] op_sel:[1,0,0]
	v_cvt_pk_f32_fp8_e32 v[218:219], v87
	v_cvt_pk_f32_fp8_sdwa v[220:221], v87 src0_sel:WORD_1
	v_pk_fma_f32 v[210:211], v[170:171], v[218:219], v[210:211] op_sel:[1,0,0]
	v_pk_fma_f32 v[212:213], v[170:171], v[220:221], v[212:213] op_sel:[1,0,0]
	s_waitcnt vmcnt(14)
	v_cvt_pk_f32_fp8_e32 v[214:215], v88
	v_cvt_pk_f32_fp8_sdwa v[216:217], v88 src0_sel:WORD_1
	v_pk_fma_f32 v[198:199], v[172:173], v[214:215], v[198:199] op_sel_hi:[0,1,1]
	v_pk_fma_f32 v[200:201], v[172:173], v[216:217], v[200:201] op_sel_hi:[0,1,1]
	v_cvt_pk_f32_fp8_e32 v[218:219], v89
	v_cvt_pk_f32_fp8_sdwa v[220:221], v89 src0_sel:WORD_1
	v_pk_fma_f32 v[202:203], v[172:173], v[218:219], v[202:203] op_sel_hi:[0,1,1]
	v_pk_fma_f32 v[204:205], v[172:173], v[220:221], v[204:205] op_sel_hi:[0,1,1]
	v_cvt_pk_f32_fp8_e32 v[214:215], v90
	v_cvt_pk_f32_fp8_sdwa v[216:217], v90 src0_sel:WORD_1
	v_pk_fma_f32 v[206:207], v[172:173], v[214:215], v[206:207] op_sel_hi:[0,1,1]
	v_pk_fma_f32 v[208:209], v[172:173], v[216:217], v[208:209] op_sel_hi:[0,1,1]
	v_cvt_pk_f32_fp8_e32 v[218:219], v91
	v_cvt_pk_f32_fp8_sdwa v[220:221], v91 src0_sel:WORD_1
	v_pk_fma_f32 v[210:211], v[172:173], v[218:219], v[210:211] op_sel_hi:[0,1,1]
	v_pk_fma_f32 v[212:213], v[172:173], v[220:221], v[212:213] op_sel_hi:[0,1,1]
	s_waitcnt vmcnt(13)
	v_cvt_pk_f32_fp8_e32 v[214:215], v92
	v_cvt_pk_f32_fp8_sdwa v[216:217], v92 src0_sel:WORD_1
	v_pk_fma_f32 v[198:199], v[172:173], v[214:215], v[198:199] op_sel:[1,0,0]
	v_pk_fma_f32 v[200:201], v[172:173], v[216:217], v[200:201] op_sel:[1,0,0]
	v_cvt_pk_f32_fp8_e32 v[218:219], v93
	v_cvt_pk_f32_fp8_sdwa v[220:221], v93 src0_sel:WORD_1
	v_pk_fma_f32 v[202:203], v[172:173], v[218:219], v[202:203] op_sel:[1,0,0]
	v_pk_fma_f32 v[204:205], v[172:173], v[220:221], v[204:205] op_sel:[1,0,0]
	v_cvt_pk_f32_fp8_e32 v[214:215], v94
	v_cvt_pk_f32_fp8_sdwa v[216:217], v94 src0_sel:WORD_1
	v_pk_fma_f32 v[206:207], v[172:173], v[214:215], v[206:207] op_sel:[1,0,0]
	v_pk_fma_f32 v[208:209], v[172:173], v[216:217], v[208:209] op_sel:[1,0,0]
	v_cvt_pk_f32_fp8_e32 v[218:219], v95
	v_cvt_pk_f32_fp8_sdwa v[220:221], v95 src0_sel:WORD_1
	v_pk_fma_f32 v[210:211], v[172:173], v[218:219], v[210:211] op_sel:[1,0,0]
	v_pk_fma_f32 v[212:213], v[172:173], v[220:221], v[212:213] op_sel:[1,0,0]
	s_waitcnt vmcnt(12)
; __device__ __forceinline__ void kv8_pv(const u32x4 (&buf)[8], f32x2v (&o2)[8], const LAS float* srow, int b) {
;     ...
; #pragma unroll
;     for (int u = 0; u < 8; ++u) {
;         const u32x4 v = buf[u]; const f32x2v pp = {p[u], p[u]};
;         o2[0] = __builtin_elementwise_fma(pp, __builtin_amdgcn_cvt_pk_f32_fp8(v.x, false), o2[0]); o2[1] = __builtin_elementwise_fma(pp, __builtin_amdgcn_cvt_pk_f32_fp8(v.x, true), o2[1]);
;         o2[2] = __builtin_elementwise_fma(pp, __builtin_amdgcn_cvt_pk_f32_fp8(v.y, false), o2[2]); o2[3] = __builtin_elementwise_fma(pp, __builtin_amdgcn_cvt_pk_f32_fp8(v.y, true), o2[3]);
;         o2[4] = __builtin_elementwise_fma(pp, __builtin_amdgcn_cvt_pk_f32_fp8(v.z, false), o2[4]); o2[5] = __builtin_elementwise_fma(pp, __builtin_amdgcn_cvt_pk_f32_fp8(v.z, true), o2[5]);
;         o2[6] = __builtin_elementwise_fma(pp, __builtin_amdgcn_cvt_pk_f32_fp8(v.w, false), o2[6]); o2[7] = __builtin_elementwise_fma(pp, __builtin_amdgcn_cvt_pk_f32_fp8(v.w, true), o2[7]);
;     }
	v_cvt_pk_f32_fp8_e32 v[214:215], v96
	v_cvt_pk_f32_fp8_sdwa v[216:217], v96 src0_sel:WORD_1
	v_pk_fma_f32 v[198:199], v[174:175], v[214:215], v[198:199] op_sel_hi:[0,1,1]
	v_pk_fma_f32 v[200:201], v[174:175], v[216:217], v[200:201] op_sel_hi:[0,1,1]
	v_cvt_pk_f32_fp8_e32 v[218:219], v97
	v_cvt_pk_f32_fp8_sdwa v[220:221], v97 src0_sel:WORD_1
	v_pk_fma_f32 v[202:203], v[174:175], v[218:219], v[202:203] op_sel_hi:[0,1,1]
	v_pk_fma_f32 v[204:205], v[174:175], v[220:221], v[204:205] op_sel_hi:[0,1,1]
	v_cvt_pk_f32_fp8_e32 v[214:215], v98
	v_cvt_pk_f32_fp8_sdwa v[216:217], v98 src0_sel:WORD_1
	v_pk_fma_f32 v[206:207], v[174:175], v[214:215], v[206:207] op_sel_hi:[0,1,1]
	v_pk_fma_f32 v[208:209], v[174:175], v[216:217], v[208:209] op_sel_hi:[0,1,1]
	v_cvt_pk_f32_fp8_e32 v[218:219], v99
	v_cvt_pk_f32_fp8_sdwa v[220:221], v99 src0_sel:WORD_1
	v_pk_fma_f32 v[210:211], v[174:175], v[218:219], v[210:211] op_sel_hi:[0,1,1]
	v_pk_fma_f32 v[212:213], v[174:175], v[220:221], v[212:213] op_sel_hi:[0,1,1]
	s_waitcnt vmcnt(11)
	v_cvt_pk_f32_fp8_e32 v[214:215], v100
	v_cvt_pk_f32_fp8_sdwa v[216:217], v100 src0_sel:WORD_1
	v_pk_fma_f32 v[198:199], v[174:175], v[214:215], v[198:199] op_sel:[1,0,0]
	v_pk_fma_f32 v[200:201], v[174:175], v[216:217], v[200:201] op_sel:[1,0,0]
	v_cvt_pk_f32_fp8_e32 v[218:219], v101
	v_cvt_pk_f32_fp8_sdwa v[220:221], v101 src0_sel:WORD_1
	v_pk_fma_f32 v[202:203], v[174:175], v[218:219], v[202:203] op_sel:[1,0,0]
	v_pk_fma_f32 v[204:205], v[174:175], v[220:221], v[204:205] op_sel:[1,0,0]
	v_cvt_pk_f32_fp8_e32 v[214:215], v102
	v_cvt_pk_f32_fp8_sdwa v[216:217], v102 src0_sel:WORD_1
	v_pk_fma_f32 v[206:207], v[174:175], v[214:215], v[206:207] op_sel:[1,0,0]
	v_pk_fma_f32 v[208:209], v[174:175], v[216:217], v[208:209] op_sel:[1,0,0]
	v_cvt_pk_f32_fp8_e32 v[218:219], v103
	v_cvt_pk_f32_fp8_sdwa v[220:221], v103 src0_sel:WORD_1
	v_pk_fma_f32 v[210:211], v[174:175], v[218:219], v[210:211] op_sel:[1,0,0]
	v_pk_fma_f32 v[212:213], v[174:175], v[220:221], v[212:213] op_sel:[1,0,0]
	s_waitcnt vmcnt(10)
	v_cvt_pk_f32_fp8_e32 v[214:215], v104
	v_cvt_pk_f32_fp8_sdwa v[216:217], v104 src0_sel:WORD_1
	v_pk_fma_f32 v[198:199], v[176:177], v[214:215], v[198:199] op_sel_hi:[0,1,1]
	v_pk_fma_f32 v[200:201], v[176:177], v[216:217], v[200:201] op_sel_hi:[0,1,1]
	v_cvt_pk_f32_fp8_e32 v[218:219], v105
	v_cvt_pk_f32_fp8_sdwa v[220:221], v105 src0_sel:WORD_1
	v_pk_fma_f32 v[202:203], v[176:177], v[218:219], v[202:203] op_sel_hi:[0,1,1]
	v_pk_fma_f32 v[204:205], v[176:177], v[220:221], v[204:205] op_sel_hi:[0,1,1]
	v_cvt_pk_f32_fp8_e32 v[214:215], v106
	v_cvt_pk_f32_fp8_sdwa v[216:217], v106 src0_sel:WORD_1
	v_pk_fma_f32 v[206:207], v[176:177], v[214:215], v[206:207] op_sel_hi:[0,1,1]
	v_pk_fma_f32 v[208:209], v[176:177], v[216:217], v[208:209] op_sel_hi:[0,1,1]
	v_cvt_pk_f32_fp8_e32 v[218:219], v107
	v_cvt_pk_f32_fp8_sdwa v[220:221], v107 src0_sel:WORD_1
	v_pk_fma_f32 v[210:211], v[176:177], v[218:219], v[210:211] op_sel_hi:[0,1,1]
	v_pk_fma_f32 v[212:213], v[176:177], v[220:221], v[212:213] op_sel_hi:[0,1,1]
	s_waitcnt vmcnt(9)
	v_cvt_pk_f32_fp8_e32 v[214:215], v108
	v_cvt_pk_f32_fp8_sdwa v[216:217], v108 src0_sel:WORD_1
	v_pk_fma_f32 v[198:199], v[176:177], v[214:215], v[198:199] op_sel:[1,0,0]
	v_pk_fma_f32 v[200:201], v[176:177], v[216:217], v[200:201] op_sel:[1,0,0]
	v_cvt_pk_f32_fp8_e32 v[218:219], v109
	v_cvt_pk_f32_fp8_sdwa v[220:221], v109 src0_sel:WORD_1
	v_pk_fma_f32 v[202:203], v[176:177], v[218:219], v[202:203] op_sel:[1,0,0]
	v_pk_fma_f32 v[204:205], v[176:177], v[220:221], v[204:205] op_sel:[1,0,0]
	v_cvt_pk_f32_fp8_e32 v[214:215], v110
	v_cvt_pk_f32_fp8_sdwa v[216:217], v110 src0_sel:WORD_1
	v_pk_fma_f32 v[206:207], v[176:177], v[214:215], v[206:207] op_sel:[1,0,0]
	v_pk_fma_f32 v[208:209], v[176:177], v[216:217], v[208:209] op_sel:[1,0,0]
	v_cvt_pk_f32_fp8_e32 v[218:219], v111
	v_cvt_pk_f32_fp8_sdwa v[220:221], v111 src0_sel:WORD_1
	v_pk_fma_f32 v[210:211], v[176:177], v[218:219], v[210:211] op_sel:[1,0,0]
	v_pk_fma_f32 v[212:213], v[176:177], v[220:221], v[212:213] op_sel:[1,0,0]
	s_waitcnt vmcnt(8)
	v_cvt_pk_f32_fp8_e32 v[214:215], v112
	v_cvt_pk_f32_fp8_sdwa v[216:217], v112 src0_sel:WORD_1
	v_pk_fma_f32 v[198:199], v[178:179], v[214:215], v[198:199] op_sel_hi:[0,1,1]
	v_pk_fma_f32 v[200:201], v[178:179], v[216:217], v[200:201] op_sel_hi:[0,1,1]
	v_cvt_pk_f32_fp8_e32 v[218:219], v113
	v_cvt_pk_f32_fp8_sdwa v[220:221], v113 src0_sel:WORD_1
	v_pk_fma_f32 v[202:203], v[178:179], v[218:219], v[202:203] op_sel_hi:[0,1,1]
	v_pk_fma_f32 v[204:205], v[178:179], v[220:221], v[204:205] op_sel_hi:[0,1,1]
	v_cvt_pk_f32_fp8_e32 v[214:215], v114
	v_cvt_pk_f32_fp8_sdwa v[216:217], v114 src0_sel:WORD_1
	v_pk_fma_f32 v[206:207], v[178:179], v[214:215], v[206:207] op_sel_hi:[0,1,1]
	v_pk_fma_f32 v[208:209], v[178:179], v[216:217], v[208:209] op_sel_hi:[0,1,1]
	v_cvt_pk_f32_fp8_e32 v[218:219], v115
	v_cvt_pk_f32_fp8_sdwa v[220:221], v115 src0_sel:WORD_1
	v_pk_fma_f32 v[210:211], v[178:179], v[218:219], v[210:211] op_sel_hi:[0,1,1]
	v_pk_fma_f32 v[212:213], v[178:179], v[220:221], v[212:213] op_sel_hi:[0,1,1]
	s_waitcnt vmcnt(7)
	v_cvt_pk_f32_fp8_e32 v[214:215], v116
	v_cvt_pk_f32_fp8_sdwa v[216:217], v116 src0_sel:WORD_1
	v_pk_fma_f32 v[198:199], v[178:179], v[214:215], v[198:199] op_sel:[1,0,0]
	v_pk_fma_f32 v[200:201], v[178:179], v[216:217], v[200:201] op_sel:[1,0,0]
	v_cvt_pk_f32_fp8_e32 v[218:219], v117
	v_cvt_pk_f32_fp8_sdwa v[220:221], v117 src0_sel:WORD_1
	v_pk_fma_f32 v[202:203], v[178:179], v[218:219], v[202:203] op_sel:[1,0,0]
	v_pk_fma_f32 v[204:205], v[178:179], v[220:221], v[204:205] op_sel:[1,0,0]
	v_cvt_pk_f32_fp8_e32 v[214:215], v118
	v_cvt_pk_f32_fp8_sdwa v[216:217], v118 src0_sel:WORD_1
	v_pk_fma_f32 v[206:207], v[178:179], v[214:215], v[206:207] op_sel:[1,0,0]
	v_pk_fma_f32 v[208:209], v[178:179], v[216:217], v[208:209] op_sel:[1,0,0]
	v_cvt_pk_f32_fp8_e32 v[218:219], v119
	v_cvt_pk_f32_fp8_sdwa v[220:221], v119 src0_sel:WORD_1
	v_pk_fma_f32 v[210:211], v[178:179], v[218:219], v[210:211] op_sel:[1,0,0]
	v_pk_fma_f32 v[212:213], v[178:179], v[220:221], v[212:213] op_sel:[1,0,0]
	s_waitcnt vmcnt(6)
; __device__ __forceinline__ unsigned cvt_pk_bf16(float lo, float hi) { unsigned r; asm volatile("v_cvt_pk_bf16_f32 %0, %1, %2" : "=v"(r) : "v"(lo), "v"(hi)); return r; }
; __device__ __forceinline__ void kv8_pv(const u32x4 (&buf)[8], f32x2v (&o2)[8], const LAS float* srow, int b) {
;     ...
; #pragma unroll
;     for (int u = 0; u < 8; ++u) {
;         const u32x4 v = buf[u]; const f32x2v pp = {p[u], p[u]};
;         o2[0] = __builtin_elementwise_fma(pp, __builtin_amdgcn_cvt_pk_f32_fp8(v.x, false), o2[0]); o2[1] = __builtin_elementwise_fma(pp, __builtin_amdgcn_cvt_pk_f32_fp8(v.x, true), o2[1]);
;         o2[2] = __builtin_elementwise_fma(pp, __builtin_amdgcn_cvt_pk_f32_fp8(v.y, false), o2[2]); o2[3] = __builtin_elementwise_fma(pp, __builtin_amdgcn_cvt_pk_f32_fp8(v.y, true), o2[3]);
;         o2[4] = __builtin_elementwise_fma(pp, __builtin_amdgcn_cvt_pk_f32_fp8(v.z, false), o2[4]); o2[5] = __builtin_elementwise_fma(pp, __builtin_amdgcn_cvt_pk_f32_fp8(v.z, true), o2[5]);
;         o2[6] = __builtin_elementwise_fma(pp, __builtin_amdgcn_cvt_pk_f32_fp8(v.w, false), o2[6]); o2[7] = __builtin_elementwise_fma(pp, __builtin_amdgcn_cvt_pk_f32_fp8(v.w, true), o2[7]);
;     }
; __device__ __forceinline__ void attn_query8(const unsigned char* __restrict__ KV8, const bf16_t* __restrict__ Z, const int* __restrict__ SEL, bf16_t* __restrict__ YMIX, int t, LAS float* sbuf  ) {
;     ...
;     u32x4 o0, o1;
;     o0.x = cvt_pk_bf16(o[0].x, o[0].y); o0.y = cvt_pk_bf16(o[1].x, o[1].y); o0.z = cvt_pk_bf16(o[2].x, o[2].y); o0.w = cvt_pk_bf16(o[3].x, o[3].y);
;     o1.x = cvt_pk_bf16(o[4].x, o[4].y); o1.y = cvt_pk_bf16(o[5].x, o[5].y); o1.z = cvt_pk_bf16(o[6].x, o[6].y); o1.w = cvt_pk_bf16(o[7].x, o[7].y);
;     u32x4* yp = (u32x4*)(YMIX + (size_t)t * D_ + 1024 + lane * 16);
;     yp[0] = o0; yp[1] = o1;
	v_cvt_pk_f32_fp8_e32 v[214:215], v120
	v_cvt_pk_f32_fp8_sdwa v[216:217], v120 src0_sel:WORD_1
	v_pk_fma_f32 v[198:199], v[180:181], v[214:215], v[198:199] op_sel_hi:[0,1,1]
	v_pk_fma_f32 v[200:201], v[180:181], v[216:217], v[200:201] op_sel_hi:[0,1,1]
	v_cvt_pk_f32_fp8_e32 v[218:219], v121
	v_cvt_pk_f32_fp8_sdwa v[220:221], v121 src0_sel:WORD_1
	v_pk_fma_f32 v[202:203], v[180:181], v[218:219], v[202:203] op_sel_hi:[0,1,1]
	v_pk_fma_f32 v[204:205], v[180:181], v[220:221], v[204:205] op_sel_hi:[0,1,1]
	v_cvt_pk_f32_fp8_e32 v[214:215], v122
	v_cvt_pk_f32_fp8_sdwa v[216:217], v122 src0_sel:WORD_1
	v_pk_fma_f32 v[206:207], v[180:181], v[214:215], v[206:207] op_sel_hi:[0,1,1]
	v_pk_fma_f32 v[208:209], v[180:181], v[216:217], v[208:209] op_sel_hi:[0,1,1]
	v_cvt_pk_f32_fp8_e32 v[218:219], v123
	v_cvt_pk_f32_fp8_sdwa v[220:221], v123 src0_sel:WORD_1
	v_pk_fma_f32 v[210:211], v[180:181], v[218:219], v[210:211] op_sel_hi:[0,1,1]
	v_pk_fma_f32 v[212:213], v[180:181], v[220:221], v[212:213] op_sel_hi:[0,1,1]
	s_waitcnt vmcnt(5)
	v_cvt_pk_f32_fp8_e32 v[214:215], v124
	v_cvt_pk_f32_fp8_sdwa v[216:217], v124 src0_sel:WORD_1
	v_pk_fma_f32 v[198:199], v[180:181], v[214:215], v[198:199] op_sel:[1,0,0]
	v_pk_fma_f32 v[200:201], v[180:181], v[216:217], v[200:201] op_sel:[1,0,0]
	v_cvt_pk_f32_fp8_e32 v[218:219], v125
	v_cvt_pk_f32_fp8_sdwa v[220:221], v125 src0_sel:WORD_1
	v_pk_fma_f32 v[202:203], v[180:181], v[218:219], v[202:203] op_sel:[1,0,0]
	v_pk_fma_f32 v[204:205], v[180:181], v[220:221], v[204:205] op_sel:[1,0,0]
	v_cvt_pk_f32_fp8_e32 v[214:215], v126
	v_cvt_pk_f32_fp8_sdwa v[216:217], v126 src0_sel:WORD_1
	v_pk_fma_f32 v[206:207], v[180:181], v[214:215], v[206:207] op_sel:[1,0,0]
	v_pk_fma_f32 v[208:209], v[180:181], v[216:217], v[208:209] op_sel:[1,0,0]
	v_cvt_pk_f32_fp8_e32 v[218:219], v127
	v_cvt_pk_f32_fp8_sdwa v[220:221], v127 src0_sel:WORD_1
	v_pk_fma_f32 v[210:211], v[180:181], v[218:219], v[210:211] op_sel:[1,0,0]
	v_pk_fma_f32 v[212:213], v[180:181], v[220:221], v[212:213] op_sel:[1,0,0]
	v_add_f32_dpp v198, v198, v198 row_ror:8 row_mask:0xf bank_mask:0xf
	v_add_f32_dpp v199, v199, v199 row_ror:8 row_mask:0xf bank_mask:0xf
	v_add_f32_dpp v200, v200, v200 row_ror:8 row_mask:0xf bank_mask:0xf
	v_add_f32_dpp v201, v201, v201 row_ror:8 row_mask:0xf bank_mask:0xf
	v_add_f32_dpp v202, v202, v202 row_ror:8 row_mask:0xf bank_mask:0xf
	v_add_f32_dpp v203, v203, v203 row_ror:8 row_mask:0xf bank_mask:0xf
	v_add_f32_dpp v204, v204, v204 row_ror:8 row_mask:0xf bank_mask:0xf
	v_add_f32_dpp v205, v205, v205 row_ror:8 row_mask:0xf bank_mask:0xf
	v_add_f32_dpp v206, v206, v206 row_ror:8 row_mask:0xf bank_mask:0xf
	v_add_f32_dpp v207, v207, v207 row_ror:8 row_mask:0xf bank_mask:0xf
	v_add_f32_dpp v208, v208, v208 row_ror:8 row_mask:0xf bank_mask:0xf
	v_add_f32_dpp v209, v209, v209 row_ror:8 row_mask:0xf bank_mask:0xf
	v_add_f32_dpp v210, v210, v210 row_ror:8 row_mask:0xf bank_mask:0xf
	v_add_f32_dpp v211, v211, v211 row_ror:8 row_mask:0xf bank_mask:0xf
	v_add_f32_dpp v212, v212, v212 row_ror:8 row_mask:0xf bank_mask:0xf
	v_add_f32_dpp v213, v213, v213 row_ror:8 row_mask:0xf bank_mask:0xf
	ds_bpermute_b32 v214, v140, v198
	ds_bpermute_b32 v215, v140, v199
	ds_bpermute_b32 v216, v140, v200
	ds_bpermute_b32 v217, v140, v201
	ds_bpermute_b32 v218, v140, v202
	ds_bpermute_b32 v219, v140, v203
	ds_bpermute_b32 v220, v140, v204
	ds_bpermute_b32 v221, v140, v205
	ds_bpermute_b32 v222, v140, v206
	ds_bpermute_b32 v223, v140, v207
	ds_bpermute_b32 v224, v140, v208
	ds_bpermute_b32 v225, v140, v209
	ds_bpermute_b32 v226, v140, v210
	ds_bpermute_b32 v227, v140, v211
	ds_bpermute_b32 v228, v140, v212
	ds_bpermute_b32 v229, v140, v213
	s_waitcnt lgkmcnt(0)
	v_add_f32_e32 v198, v198, v214
	v_add_f32_e32 v199, v199, v215
	v_add_f32_e32 v200, v200, v216
	v_add_f32_e32 v201, v201, v217
	v_add_f32_e32 v202, v202, v218
	v_add_f32_e32 v203, v203, v219
	v_add_f32_e32 v204, v204, v220
	v_add_f32_e32 v205, v205, v221
	v_add_f32_e32 v206, v206, v222
	v_add_f32_e32 v207, v207, v223
	v_add_f32_e32 v208, v208, v224
	v_add_f32_e32 v209, v209, v225
	v_add_f32_e32 v210, v210, v226
	v_add_f32_e32 v211, v211, v227
	v_add_f32_e32 v212, v212, v228
	v_add_f32_e32 v213, v213, v229
	ds_bpermute_b32 v214, v141, v198
	ds_bpermute_b32 v215, v141, v199
	ds_bpermute_b32 v216, v141, v200
	ds_bpermute_b32 v217, v141, v201
	ds_bpermute_b32 v218, v141, v202
	ds_bpermute_b32 v219, v141, v203
	ds_bpermute_b32 v220, v141, v204
	ds_bpermute_b32 v221, v141, v205
	ds_bpermute_b32 v222, v141, v206
	ds_bpermute_b32 v223, v141, v207
	ds_bpermute_b32 v224, v141, v208
	ds_bpermute_b32 v225, v141, v209
	ds_bpermute_b32 v226, v141, v210
	ds_bpermute_b32 v227, v141, v211
	ds_bpermute_b32 v228, v141, v212
	ds_bpermute_b32 v229, v141, v213
	s_waitcnt lgkmcnt(0)
	v_add_f32_e32 v198, v198, v214
	v_add_f32_e32 v199, v199, v215
	v_add_f32_e32 v200, v200, v216
	v_add_f32_e32 v201, v201, v217
	v_add_f32_e32 v202, v202, v218
	v_add_f32_e32 v203, v203, v219
	v_add_f32_e32 v204, v204, v220
	v_add_f32_e32 v205, v205, v221
	v_add_f32_e32 v206, v206, v222
	v_add_f32_e32 v207, v207, v223
	v_add_f32_e32 v208, v208, v224
	v_add_f32_e32 v209, v209, v225
	v_add_f32_e32 v210, v210, v226
	v_add_f32_e32 v211, v211, v227
	v_add_f32_e32 v212, v212, v228
	v_add_f32_e32 v213, v213, v229
	s_ashr_i32 s81, s80, 31
	s_lshl_b64 s[10:11], s[80:81], 12
	s_add_u32 s10, s14, s10
	s_addc_u32 s11, s15, s11
	v_mul_f32_e32 v198, v198, v149
	v_mul_f32_e32 v199, v199, v149
	v_mul_f32_e32 v200, v200, v149
	v_mul_f32_e32 v201, v201, v149
	v_mul_f32_e32 v202, v202, v149
	v_mul_f32_e32 v203, v203, v149
	v_mul_f32_e32 v204, v204, v149
	v_mul_f32_e32 v205, v205, v149
	v_mul_f32_e32 v206, v206, v149
	v_mul_f32_e32 v207, v207, v149
	v_mul_f32_e32 v208, v208, v149
	v_mul_f32_e32 v209, v209, v149
	v_mul_f32_e32 v210, v210, v149
	v_mul_f32_e32 v211, v211, v149
	v_mul_f32_e32 v212, v212, v149
	v_mul_f32_e32 v213, v213, v149
	v_cvt_pk_bf16_f32 v214, v198, v199
	v_cvt_pk_bf16_f32 v215, v200, v201
	v_cvt_pk_bf16_f32 v216, v202, v203
	v_cvt_pk_bf16_f32 v217, v204, v205
	v_cvt_pk_bf16_f32 v218, v206, v207
	v_cvt_pk_bf16_f32 v219, v208, v209
	v_cvt_pk_bf16_f32 v220, v210, v211
	v_cvt_pk_bf16_f32 v221, v212, v213
	v_cmp_gt_u32_e32 vcc, 8, v144
	s_and_saveexec_b64 s[12:13], vcc
	global_store_dwordx4 v146, v[214:217], s[10:11] offset:2048
	global_store_dwordx4 v146, v[218:221], s[10:11] offset:2064
	s_mov_b64 exec, s[12:13]
	s_addk_i32 s80, 0x100
	s_cmpk_gt_i32 s80, 0x3fff
	s_cbranch_scc0 .Latt_unit
